# v43 + removed 32 provably redundant s_waitcnt lgkmcnt(0) that directly follow the phase barrier in the GEMM K-loops
# baseline (speedup 1.0000x reference)
; #define PG8_STAGE(bufoff, gbase, voff) do { _Pragma("unroll") for (int _i = 0; _i < 2; ++_i) \
;         __builtin_amdgcn_global_load_lds((const unsigned*)((const char*)(gbase) + (voff)[_i]), (LAS unsigned*)(lds + (bufoff) + ldsw + _i * 8192), 16, 0, 0); } while (0)
; #define PG8_LDA(dst, b, h) do { _Pragma("unroll") for (int m = 0; m < 4; ++m) _Pragma("unroll") for (int k = 0; k < 2; ++k) dst[m][k] = *(const LAS bf16x8*)(lds + PG8_SA(b, h) + aoff + m * 2048 + k * 1024); } while (0)
; #define PG8_LDB(dst, b, h) do { _Pragma("unroll") for (int n = 0; n < 2; ++n) _Pragma("unroll") for (int k = 0; k < 2; ++k) dst[n][k] = *(const LAS bf16x8*)(lds + PG8_SB(b, h) + boff + n * 2048 + k * 1024); } while (0)
; #define PG8_MMA(ai, bj, At, Bt) do { __builtin_amdgcn_s_setprio(1); _Pragma("unroll") for (int m = 0; m < 4; ++m) _Pragma("unroll") for (int n = 0; n < 2; ++n) _Pragma("unroll") for (int k = 0; k < 2; ++k) \
;         acc[ai][bj][m][n] = __builtin_amdgcn_mfma_f32_16x16x32_bf16(Bt[n][k], At[m][k], acc[ai][bj][m][n], 0, 0, 0); __builtin_amdgcn_s_setprio(0); } while (0)
; #define PG8_WAIT_V(n) asm volatile("s_waitcnt vmcnt(" #n ")" ::: "memory")
; #define PG8_WAIT_L(n) asm volatile("s_waitcnt lgkmcnt(" #n ")" ::: "memory")
; #define PG8_BAR __builtin_amdgcn_s_barrier()
; #define PG8_SCHED __builtin_amdgcn_sched_barrier(0)
; template <class Epi, class Sched, bool HALFN = false>
; __device__ __forceinline__ void gemm_phase(LAS unsigned char* lds, const Gemm g, const Sched& S, const Epi& E, int wave_s) {
;     ...
;         for (int t = 0; t < nt; t += 2) {
;             const bool last = (t == nt - 2);
;             const char* a1 = cA + (size_t)(t + 1) * kstep;
;             const char* a2 = last ? nA : cA + (size_t)(t + 2) * kstep; const char* b2 = last ? nB : cB + (size_t)(t + 2) * kstep;
;             const char* a3 = a2 + kstep; const char* b3 = b2 + kstep;
;             PG8_LDB(B0, 0, 0); if (!HALFN) PG8_LDB(B1, 0, 1); PG8_SCHED; PG8_LDA(At, 0, 0); PG8_STAGE(PG8_SA(1, 1), a1 + hstep, voffA);
;             PG8_WAIT_V(8); PG8_WAIT_L(0); PG8_BAR; PG8_MMA(0, 0, At, B0); if (!HALFN) PG8_MMA(0, 1, At, B1); PG8_BAR; PG8_SCHED;
;             PG8_LDA(At, 0, 1); PG8_STAGE(PG8_SB(0, 0), b2, voffB); PG8_STAGE(PG8_SB(0, 1), b2 + bh1, voffB); PG8_STAGE(PG8_SA(0, 0), a2, voffA);
.LBB0_269:
	s_add_u32 s53, s8, 0xfffc0080
	s_addc_u32 s66, s9, -1
	s_add_i32 s82, 0, 0x10000
	s_cmp_eq_u32 s52, 12
	s_cselect_b32 s81, s5, s66
	s_cselect_b32 s80, s7, s53
	v_add_u32_e32 v18, s82, v1
	s_cselect_b32 s79, s39, s48
	s_cselect_b32 s78, s42, s47
	s_add_i32 s53, 0, 0x14000
	ds_read_b128 v[146:149], v18
	ds_read_b128 v[150:153], v18 offset:1024
	ds_read_b128 v[154:157], v18 offset:2048
	ds_read_b128 v[158:161], v18 offset:3072
	v_add_u32_e32 v18, s53, v1
	ds_read_b128 v[162:165], v18
	ds_read_b128 v[166:169], v18 offset:1024
	ds_read_b128 v[172:175], v18 offset:2048
	ds_read_b128 v[176:179], v18 offset:3072
	v_lshl_add_u64 v[196:197], s[8:9], 0, v[140:141]
	s_add_i32 m0, s67, 0xc000
	ds_read_b128 v[180:183], v170
	ds_read_b128 v[184:187], v170 offset:1024
	ds_read_b128 v[188:191], v170 offset:2048
	ds_read_b128 v[192:195], v170 offset:3072
	ds_read_b128 v[208:211], v170 offset:4096
	ds_read_b128 v[212:215], v170 offset:5120
	ds_read_b128 v[216:219], v170 offset:6144
	ds_read_b128 v[220:223], v170 offset:7168
	global_load_lds_dwordx4 v[196:197], off
	v_lshl_add_u64 v[196:197], s[8:9], 0, v[142:143]
	s_add_i32 m0, s67, 0xe000
	s_nop 0
	global_load_lds_dwordx4 v[196:197], off
	s_waitcnt vmcnt(8)
	s_waitcnt lgkmcnt(0)
	s_barrier
	s_setprio 1
	v_mfma_f32_16x16x32_bf16 v[128:131], v[146:149], v[180:183], v[128:131]
	v_mfma_f32_16x16x32_bf16 v[124:127], v[154:157], v[180:183], v[124:127]
	v_mfma_f32_16x16x32_bf16 v[112:115], v[146:149], v[188:191], v[112:115]
	v_mfma_f32_16x16x32_bf16 v[108:111], v[154:157], v[188:191], v[108:111]
	v_mfma_f32_16x16x32_bf16 v[96:99], v[146:149], v[208:211], v[96:99]
	v_mfma_f32_16x16x32_bf16 v[92:95], v[154:157], v[208:211], v[92:95]
	v_mfma_f32_16x16x32_bf16 v[80:83], v[146:149], v[216:219], v[80:83]
	v_mfma_f32_16x16x32_bf16 v[76:79], v[154:157], v[216:219], v[76:79]
	v_mfma_f32_16x16x32_bf16 v[128:131], v[150:153], v[184:187], v[128:131]
	v_mfma_f32_16x16x32_bf16 v[124:127], v[158:161], v[184:187], v[124:127]
	v_mfma_f32_16x16x32_bf16 v[112:115], v[150:153], v[192:195], v[112:115]
	v_mfma_f32_16x16x32_bf16 v[108:111], v[158:161], v[192:195], v[108:111]
	v_mfma_f32_16x16x32_bf16 v[96:99], v[150:153], v[212:215], v[96:99]
	v_mfma_f32_16x16x32_bf16 v[92:95], v[158:161], v[212:215], v[92:95]
	v_mfma_f32_16x16x32_bf16 v[80:83], v[150:153], v[220:223], v[80:83]
	v_mfma_f32_16x16x32_bf16 v[76:79], v[158:161], v[220:223], v[76:79]
	v_mfma_f32_16x16x32_bf16 v[120:123], v[162:165], v[180:183], v[120:123]
	v_mfma_f32_16x16x32_bf16 v[116:119], v[172:175], v[180:183], v[116:119]
	v_mfma_f32_16x16x32_bf16 v[104:107], v[162:165], v[188:191], v[104:107]
	v_mfma_f32_16x16x32_bf16 v[100:103], v[172:175], v[188:191], v[100:103]
	v_mfma_f32_16x16x32_bf16 v[88:91], v[162:165], v[208:211], v[88:91]
	v_mfma_f32_16x16x32_bf16 v[84:87], v[172:175], v[208:211], v[84:87]
	v_mfma_f32_16x16x32_bf16 v[72:75], v[162:165], v[216:219], v[72:75]
	v_mfma_f32_16x16x32_bf16 v[68:71], v[172:175], v[216:219], v[68:71]
	v_mfma_f32_16x16x32_bf16 v[120:123], v[166:169], v[184:187], v[120:123]
	v_mfma_f32_16x16x32_bf16 v[116:119], v[176:179], v[184:187], v[116:119]
	v_mfma_f32_16x16x32_bf16 v[104:107], v[166:169], v[192:195], v[104:107]
	v_mfma_f32_16x16x32_bf16 v[100:103], v[176:179], v[192:195], v[100:103]
	v_mfma_f32_16x16x32_bf16 v[88:91], v[166:169], v[212:215], v[88:91]
	v_mfma_f32_16x16x32_bf16 v[84:87], v[176:179], v[212:215], v[84:87]
	v_mfma_f32_16x16x32_bf16 v[72:75], v[166:169], v[220:223], v[72:75]
	v_mfma_f32_16x16x32_bf16 v[68:71], v[176:179], v[220:223], v[68:71]
	s_setprio 0
	s_barrier
	s_add_i32 s66, s82, s64
	v_lshl_add_u64 v[196:197], s[78:79], 0, v[134:135]
	s_mov_b32 m0, s66
	ds_read_b128 v[180:183], v170 offset:16384
	ds_read_b128 v[184:187], v170 offset:17408
	ds_read_b128 v[188:191], v170 offset:18432
	ds_read_b128 v[192:195], v170 offset:19456
	ds_read_b128 v[208:211], v170 offset:20480
	ds_read_b128 v[212:215], v170 offset:21504
	ds_read_b128 v[216:219], v170 offset:22528
	ds_read_b128 v[220:223], v170 offset:23552
	global_load_lds_dwordx4 v[196:197], off
	s_add_i32 m0, s66, 0x2000
	s_add_u32 s82, s78, 0x40000
	v_lshl_add_u64 v[224:225], s[78:79], 0, v[138:139]
	s_addc_u32 s83, s79, 0
	s_add_i32 s53, s53, s64
	global_load_lds_dwordx4 v[224:225], off
	v_lshl_add_u64 v[226:227], s[82:83], 0, v[134:135]
	s_mov_b32 m0, s53
	v_lshl_add_u64 v[228:229], s[80:81], 0, v[136:137]
	global_load_lds_dwordx4 v[226:227], off
	v_lshl_add_u64 v[226:227], s[82:83], 0, v[138:139]
	s_add_i32 m0, s53, 0x2000
	s_nop 0
	global_load_lds_dwordx4 v[226:227], off
	v_lshl_add_u64 v[226:227], s[80:81], 0, v[132:133]
	s_mov_b32 m0, s67
	s_nop 0
	global_load_lds_dwordx4 v[226:227], off
	s_mov_b32 m0, s70
	s_nop 0
	global_load_lds_dwordx4 v[228:229], off
	s_waitcnt vmcnt(8)
	s_waitcnt lgkmcnt(0)
	s_barrier
; #define PG8_STAGE(bufoff, gbase, voff) do { _Pragma("unroll") for (int _i = 0; _i < 2; ++_i) \
;         __builtin_amdgcn_global_load_lds((const unsigned*)((const char*)(gbase) + (voff)[_i]), (LAS unsigned*)(lds + (bufoff) + ldsw + _i * 8192), 16, 0, 0); } while (0)
; #define PG8_LDA(dst, b, h) do { _Pragma("unroll") for (int m = 0; m < 4; ++m) _Pragma("unroll") for (int k = 0; k < 2; ++k) dst[m][k] = *(const LAS bf16x8*)(lds + PG8_SA(b, h) + aoff + m * 2048 + k * 1024); } while (0)
; #define PG8_LDB(dst, b, h) do { _Pragma("unroll") for (int n = 0; n < 2; ++n) _Pragma("unroll") for (int k = 0; k < 2; ++k) dst[n][k] = *(const LAS bf16x8*)(lds + PG8_SB(b, h) + boff + n * 2048 + k * 1024); } while (0)
; #define PG8_MMA(ai, bj, At, Bt) do { __builtin_amdgcn_s_setprio(1); _Pragma("unroll") for (int m = 0; m < 4; ++m) _Pragma("unroll") for (int n = 0; n < 2; ++n) _Pragma("unroll") for (int k = 0; k < 2; ++k) \
;         acc[ai][bj][m][n] = __builtin_amdgcn_mfma_f32_16x16x32_bf16(Bt[n][k], At[m][k], acc[ai][bj][m][n], 0, 0, 0); __builtin_amdgcn_s_setprio(0); } while (0)
; #define PG8_WAIT_V(n) asm volatile("s_waitcnt vmcnt(" #n ")" ::: "memory")
; #define PG8_WAIT_L(n) asm volatile("s_waitcnt lgkmcnt(" #n ")" ::: "memory")
; #define PG8_BAR __builtin_amdgcn_s_barrier()
; #define PG8_SCHED __builtin_amdgcn_sched_barrier(0)
; template <class Epi, class Sched, bool HALFN = false>
; __device__ __forceinline__ void gemm_phase(LAS unsigned char* lds, const Gemm g, const Sched& S, const Epi& E, int wave_s) {
;     ...
;             PG8_WAIT_V(8); PG8_WAIT_L(0); PG8_BAR; PG8_MMA(1, 0, At, B0); if (!HALFN) PG8_MMA(1, 1, At, B1); PG8_BAR; PG8_SCHED;
;             PG8_LDB(B0, 1, 0); if (!HALFN) PG8_LDB(B1, 1, 1); PG8_SCHED; PG8_LDA(At, 1, 0); PG8_STAGE(PG8_SA(0, 1), a2 + hstep, voffA);
;             PG8_WAIT_V(8); PG8_WAIT_L(0); PG8_BAR; PG8_MMA(0, 0, At, B0); if (!HALFN) PG8_MMA(0, 1, At, B1); PG8_BAR; PG8_SCHED;
	s_setprio 1
	v_mfma_f32_16x16x32_bf16 v[64:67], v[146:149], v[180:183], v[64:67]
	v_mfma_f32_16x16x32_bf16 v[60:63], v[154:157], v[180:183], v[60:63]
	v_mfma_f32_16x16x32_bf16 v[48:51], v[146:149], v[188:191], v[48:51]
	v_mfma_f32_16x16x32_bf16 v[44:47], v[154:157], v[188:191], v[44:47]
	v_mfma_f32_16x16x32_bf16 v[32:35], v[146:149], v[208:211], v[32:35]
	v_mfma_f32_16x16x32_bf16 v[28:31], v[154:157], v[208:211], v[28:31]
	v_mfma_f32_16x16x32_bf16 v[14:17], v[146:149], v[216:219], v[14:17]
	v_mfma_f32_16x16x32_bf16 v[10:13], v[154:157], v[216:219], v[10:13]
	v_mfma_f32_16x16x32_bf16 v[64:67], v[150:153], v[184:187], v[64:67]
	v_mfma_f32_16x16x32_bf16 v[60:63], v[158:161], v[184:187], v[60:63]
	v_mfma_f32_16x16x32_bf16 v[48:51], v[150:153], v[192:195], v[48:51]
	v_mfma_f32_16x16x32_bf16 v[44:47], v[158:161], v[192:195], v[44:47]
	v_mfma_f32_16x16x32_bf16 v[32:35], v[150:153], v[212:215], v[32:35]
	v_mfma_f32_16x16x32_bf16 v[28:31], v[158:161], v[212:215], v[28:31]
	v_mfma_f32_16x16x32_bf16 v[14:17], v[150:153], v[220:223], v[14:17]
	v_mfma_f32_16x16x32_bf16 v[10:13], v[158:161], v[220:223], v[10:13]
	v_mfma_f32_16x16x32_bf16 v[56:59], v[162:165], v[180:183], v[56:59]
	v_mfma_f32_16x16x32_bf16 v[52:55], v[172:175], v[180:183], v[52:55]
	v_mfma_f32_16x16x32_bf16 v[40:43], v[162:165], v[188:191], v[40:43]
	v_mfma_f32_16x16x32_bf16 v[36:39], v[172:175], v[188:191], v[36:39]
	v_mfma_f32_16x16x32_bf16 v[24:27], v[162:165], v[208:211], v[24:27]
	v_mfma_f32_16x16x32_bf16 v[20:23], v[172:175], v[208:211], v[20:23]
	v_mfma_f32_16x16x32_bf16 v[6:9], v[162:165], v[216:219], v[6:9]
	v_mfma_f32_16x16x32_bf16 v[2:5], v[172:175], v[216:219], v[2:5]
	v_mfma_f32_16x16x32_bf16 v[56:59], v[166:169], v[184:187], v[56:59]
	v_mfma_f32_16x16x32_bf16 v[52:55], v[176:179], v[184:187], v[52:55]
	v_mfma_f32_16x16x32_bf16 v[40:43], v[166:169], v[192:195], v[40:43]
	v_mfma_f32_16x16x32_bf16 v[36:39], v[176:179], v[192:195], v[36:39]
	v_mfma_f32_16x16x32_bf16 v[24:27], v[166:169], v[212:215], v[24:27]
	v_mfma_f32_16x16x32_bf16 v[20:23], v[176:179], v[212:215], v[20:23]
	v_mfma_f32_16x16x32_bf16 v[6:9], v[166:169], v[220:223], v[6:9]
	v_mfma_f32_16x16x32_bf16 v[2:5], v[176:179], v[220:223], v[2:5]
	s_setprio 0
	s_barrier
	s_add_i32 s53, 0, 0x18000
	v_add_u32_e32 v18, s53, v1
	s_add_i32 s66, 0, 0x1c000
	ds_read_b128 v[146:149], v18
	ds_read_b128 v[150:153], v18 offset:1024
	ds_read_b128 v[154:157], v18 offset:2048
	ds_read_b128 v[158:161], v18 offset:3072
	v_add_u32_e32 v18, s66, v1
	ds_read_b128 v[162:165], v18
	ds_read_b128 v[166:169], v18 offset:1024
	ds_read_b128 v[172:175], v18 offset:2048
	ds_read_b128 v[176:179], v18 offset:3072
	s_add_u32 s80, s80, 0x40000
	s_addc_u32 s81, s81, 0
	s_mov_b32 m0, s71
	v_lshl_add_u64 v[230:231], s[80:81], 0, v[132:133]
	ds_read_b128 v[180:183], v170 offset:32768
	ds_read_b128 v[184:187], v170 offset:33792
	ds_read_b128 v[188:191], v170 offset:34816
	ds_read_b128 v[192:195], v170 offset:35840
	ds_read_b128 v[208:211], v170 offset:36864
	ds_read_b128 v[212:215], v170 offset:37888
	ds_read_b128 v[216:219], v170 offset:38912
	ds_read_b128 v[220:223], v170 offset:39936
	global_load_lds_dwordx4 v[230:231], off
	v_lshl_add_u64 v[230:231], s[80:81], 0, v[136:137]
	s_mov_b32 m0, s74
	s_nop 0
	global_load_lds_dwordx4 v[230:231], off
	s_waitcnt vmcnt(8)
	s_waitcnt lgkmcnt(0)
	s_barrier
	s_setprio 1
	v_mfma_f32_16x16x32_bf16 v[128:131], v[146:149], v[180:183], v[128:131]
	v_mfma_f32_16x16x32_bf16 v[124:127], v[154:157], v[180:183], v[124:127]
	v_mfma_f32_16x16x32_bf16 v[112:115], v[146:149], v[188:191], v[112:115]
	v_mfma_f32_16x16x32_bf16 v[108:111], v[154:157], v[188:191], v[108:111]
	v_mfma_f32_16x16x32_bf16 v[96:99], v[146:149], v[208:211], v[96:99]
	v_mfma_f32_16x16x32_bf16 v[92:95], v[154:157], v[208:211], v[92:95]
	v_mfma_f32_16x16x32_bf16 v[80:83], v[146:149], v[216:219], v[80:83]
	v_mfma_f32_16x16x32_bf16 v[76:79], v[154:157], v[216:219], v[76:79]
	v_mfma_f32_16x16x32_bf16 v[128:131], v[150:153], v[184:187], v[128:131]
	v_mfma_f32_16x16x32_bf16 v[124:127], v[158:161], v[184:187], v[124:127]
	v_mfma_f32_16x16x32_bf16 v[112:115], v[150:153], v[192:195], v[112:115]
	v_mfma_f32_16x16x32_bf16 v[108:111], v[158:161], v[192:195], v[108:111]
	v_mfma_f32_16x16x32_bf16 v[96:99], v[150:153], v[212:215], v[96:99]
	v_mfma_f32_16x16x32_bf16 v[92:95], v[158:161], v[212:215], v[92:95]
	v_mfma_f32_16x16x32_bf16 v[80:83], v[150:153], v[220:223], v[80:83]
	v_mfma_f32_16x16x32_bf16 v[76:79], v[158:161], v[220:223], v[76:79]
	v_mfma_f32_16x16x32_bf16 v[120:123], v[162:165], v[180:183], v[120:123]
	v_mfma_f32_16x16x32_bf16 v[116:119], v[172:175], v[180:183], v[116:119]
	v_mfma_f32_16x16x32_bf16 v[104:107], v[162:165], v[188:191], v[104:107]
	v_mfma_f32_16x16x32_bf16 v[100:103], v[172:175], v[188:191], v[100:103]
	v_mfma_f32_16x16x32_bf16 v[88:91], v[162:165], v[208:211], v[88:91]
	v_mfma_f32_16x16x32_bf16 v[84:87], v[172:175], v[208:211], v[84:87]
	v_mfma_f32_16x16x32_bf16 v[72:75], v[162:165], v[216:219], v[72:75]
	v_mfma_f32_16x16x32_bf16 v[68:71], v[172:175], v[216:219], v[68:71]
	v_mfma_f32_16x16x32_bf16 v[120:123], v[166:169], v[184:187], v[120:123]
	v_mfma_f32_16x16x32_bf16 v[116:119], v[176:179], v[184:187], v[116:119]
	v_mfma_f32_16x16x32_bf16 v[104:107], v[166:169], v[192:195], v[104:107]
	v_mfma_f32_16x16x32_bf16 v[100:103], v[176:179], v[192:195], v[100:103]
	v_mfma_f32_16x16x32_bf16 v[88:91], v[166:169], v[212:215], v[88:91]
	v_mfma_f32_16x16x32_bf16 v[84:87], v[176:179], v[212:215], v[84:87]
	v_mfma_f32_16x16x32_bf16 v[72:75], v[166:169], v[220:223], v[72:75]
	v_mfma_f32_16x16x32_bf16 v[68:71], v[176:179], v[220:223], v[68:71]
	s_setprio 0
	s_barrier
; #define PG8_STAGE(bufoff, gbase, voff) do { _Pragma("unroll") for (int _i = 0; _i < 2; ++_i) \
;         __builtin_amdgcn_global_load_lds((const unsigned*)((const char*)(gbase) + (voff)[_i]), (LAS unsigned*)(lds + (bufoff) + ldsw + _i * 8192), 16, 0, 0); } while (0)
; #define PG8_LDA(dst, b, h) do { _Pragma("unroll") for (int m = 0; m < 4; ++m) _Pragma("unroll") for (int k = 0; k < 2; ++k) dst[m][k] = *(const LAS bf16x8*)(lds + PG8_SA(b, h) + aoff + m * 2048 + k * 1024); } while (0)
; #define PG8_MMA(ai, bj, At, Bt) do { __builtin_amdgcn_s_setprio(1); _Pragma("unroll") for (int m = 0; m < 4; ++m) _Pragma("unroll") for (int n = 0; n < 2; ++n) _Pragma("unroll") for (int k = 0; k < 2; ++k) \
;         acc[ai][bj][m][n] = __builtin_amdgcn_mfma_f32_16x16x32_bf16(Bt[n][k], At[m][k], acc[ai][bj][m][n], 0, 0, 0); __builtin_amdgcn_s_setprio(0); } while (0)
; #define PG8_WAIT_V(n) asm volatile("s_waitcnt vmcnt(" #n ")" ::: "memory")
; #define PG8_WAIT_L(n) asm volatile("s_waitcnt lgkmcnt(" #n ")" ::: "memory")
; #define PG8_BAR __builtin_amdgcn_s_barrier()
; #define PG8_SCHED __builtin_amdgcn_sched_barrier(0)
; template <class Epi, class Sched, bool HALFN = false>
; __device__ __forceinline__ void gemm_phase(LAS unsigned char* lds, const Gemm g, const Sched& S, const Epi& E, int wave_s) {
;     ...
;             PG8_LDA(At, 1, 1); PG8_STAGE(PG8_SB(1, 0), b3, voffB); PG8_STAGE(PG8_SB(1, 1), b3 + bh1, voffB); PG8_STAGE(PG8_SA(1, 0), a3, voffA);
;             PG8_WAIT_V(8); PG8_WAIT_L(0); PG8_BAR; PG8_MMA(1, 0, At, B0); if (!HALFN) PG8_MMA(1, 1, At, B1); PG8_BAR; PG8_SCHED;
;         }
;         if (wr == 0) PG8_BAR;
	s_add_i32 s53, s53, s64
	v_lshl_add_u64 v[196:197], v[196:197], 0, s[50:51]
	s_mov_b32 m0, s53
	ds_read_b128 v[180:183], v170 offset:49152
	ds_read_b128 v[184:187], v170 offset:50176
	ds_read_b128 v[188:191], v170 offset:51200
	ds_read_b128 v[192:195], v170 offset:52224
	ds_read_b128 v[208:211], v170 offset:53248
	ds_read_b128 v[212:215], v170 offset:54272
	ds_read_b128 v[216:219], v170 offset:55296
	ds_read_b128 v[220:223], v170 offset:56320
	global_load_lds_dwordx4 v[196:197], off
	s_add_i32 m0, s53, 0x2000
	s_add_u32 s78, s78, 0x40080
	v_lshl_add_u64 v[196:197], v[224:225], 0, s[50:51]
	s_addc_u32 s79, s79, 0
	s_add_i32 s53, s66, s64
	global_load_lds_dwordx4 v[196:197], off
	v_lshl_add_u64 v[196:197], s[78:79], 0, v[134:135]
	s_mov_b32 m0, s53
	s_nop 0
	global_load_lds_dwordx4 v[196:197], off
	v_lshl_add_u64 v[196:197], s[78:79], 0, v[138:139]
	s_add_i32 m0, s53, 0x2000
	s_nop 0
	global_load_lds_dwordx4 v[196:197], off
	v_lshl_add_u64 v[196:197], v[226:227], 0, s[50:51]
	s_mov_b32 m0, s75
	s_nop 0
	global_load_lds_dwordx4 v[196:197], off
	v_lshl_add_u64 v[196:197], v[228:229], 0, s[50:51]
	s_mov_b32 m0, s88
	s_nop 0
	global_load_lds_dwordx4 v[196:197], off
	s_waitcnt vmcnt(8)
	s_waitcnt lgkmcnt(0)
	s_barrier
	s_setprio 1
	v_mfma_f32_16x16x32_bf16 v[64:67], v[146:149], v[180:183], v[64:67]
	v_mfma_f32_16x16x32_bf16 v[60:63], v[154:157], v[180:183], v[60:63]
	v_mfma_f32_16x16x32_bf16 v[48:51], v[146:149], v[188:191], v[48:51]
	v_mfma_f32_16x16x32_bf16 v[44:47], v[154:157], v[188:191], v[44:47]
	v_mfma_f32_16x16x32_bf16 v[32:35], v[146:149], v[208:211], v[32:35]
	v_mfma_f32_16x16x32_bf16 v[28:31], v[154:157], v[208:211], v[28:31]
	v_mfma_f32_16x16x32_bf16 v[14:17], v[146:149], v[216:219], v[14:17]
	v_mfma_f32_16x16x32_bf16 v[10:13], v[154:157], v[216:219], v[10:13]
	v_mfma_f32_16x16x32_bf16 v[64:67], v[150:153], v[184:187], v[64:67]
	v_mfma_f32_16x16x32_bf16 v[60:63], v[158:161], v[184:187], v[60:63]
	v_mfma_f32_16x16x32_bf16 v[48:51], v[150:153], v[192:195], v[48:51]
	v_mfma_f32_16x16x32_bf16 v[44:47], v[158:161], v[192:195], v[44:47]
	v_mfma_f32_16x16x32_bf16 v[32:35], v[150:153], v[212:215], v[32:35]
	v_mfma_f32_16x16x32_bf16 v[28:31], v[158:161], v[212:215], v[28:31]
	v_mfma_f32_16x16x32_bf16 v[14:17], v[150:153], v[220:223], v[14:17]
	v_mfma_f32_16x16x32_bf16 v[10:13], v[158:161], v[220:223], v[10:13]
	v_mfma_f32_16x16x32_bf16 v[56:59], v[162:165], v[180:183], v[56:59]
	v_mfma_f32_16x16x32_bf16 v[52:55], v[172:175], v[180:183], v[52:55]
	v_mfma_f32_16x16x32_bf16 v[40:43], v[162:165], v[188:191], v[40:43]
	v_mfma_f32_16x16x32_bf16 v[36:39], v[172:175], v[188:191], v[36:39]
	v_mfma_f32_16x16x32_bf16 v[24:27], v[162:165], v[208:211], v[24:27]
	v_mfma_f32_16x16x32_bf16 v[20:23], v[172:175], v[208:211], v[20:23]
	v_mfma_f32_16x16x32_bf16 v[6:9], v[162:165], v[216:219], v[6:9]
	v_mfma_f32_16x16x32_bf16 v[2:5], v[172:175], v[216:219], v[2:5]
	v_mfma_f32_16x16x32_bf16 v[56:59], v[166:169], v[184:187], v[56:59]
	v_mfma_f32_16x16x32_bf16 v[52:55], v[176:179], v[184:187], v[52:55]
	v_mfma_f32_16x16x32_bf16 v[40:43], v[166:169], v[192:195], v[40:43]
	v_mfma_f32_16x16x32_bf16 v[36:39], v[176:179], v[192:195], v[36:39]
	v_mfma_f32_16x16x32_bf16 v[24:27], v[166:169], v[212:215], v[24:27]
	v_mfma_f32_16x16x32_bf16 v[20:23], v[176:179], v[212:215], v[20:23]
	v_mfma_f32_16x16x32_bf16 v[6:9], v[166:169], v[220:223], v[6:9]
	v_mfma_f32_16x16x32_bf16 v[2:5], v[176:179], v[220:223], v[2:5]
	s_setprio 0
	s_barrier
	s_add_i32 s52, s52, 2
	s_add_u32 s8, s8, 0x100
	s_addc_u32 s9, s9, 0
	s_add_u32 s47, s47, 0x100
	s_addc_u32 s48, s48, 0
	s_cmp_gt_u32 s52, 13
	s_cbranch_scc0 .LBB0_269
	s_and_b64 vcc, exec, s[26:27]
	s_cbranch_vccz .LBB0_272
	s_barrier

; #define PG8_STAGE(bufoff, gbase, voff) do { _Pragma("unroll") for (int _i = 0; _i < 2; ++_i) \
;         __builtin_amdgcn_global_load_lds((const unsigned*)((const char*)(gbase) + (voff)[_i]), (LAS unsigned*)(lds + (bufoff) + ldsw + _i * 8192), 16, 0, 0); } while (0)
; #define PG8_LDA(dst, b, h) do { _Pragma("unroll") for (int m = 0; m < 4; ++m) _Pragma("unroll") for (int k = 0; k < 2; ++k) dst[m][k] = *(const LAS bf16x8*)(lds + PG8_SA(b, h) + aoff + m * 2048 + k * 1024); } while (0)
; #define PG8_LDB(dst, b, h) do { _Pragma("unroll") for (int n = 0; n < 2; ++n) _Pragma("unroll") for (int k = 0; k < 2; ++k) dst[n][k] = *(const LAS bf16x8*)(lds + PG8_SB(b, h) + boff + n * 2048 + k * 1024); } while (0)
; #define PG8_MMA(ai, bj, At, Bt) do { __builtin_amdgcn_s_setprio(1); _Pragma("unroll") for (int m = 0; m < 4; ++m) _Pragma("unroll") for (int n = 0; n < 2; ++n) _Pragma("unroll") for (int k = 0; k < 2; ++k) \
;         acc[ai][bj][m][n] = __builtin_amdgcn_mfma_f32_16x16x32_bf16(Bt[n][k], At[m][k], acc[ai][bj][m][n], 0, 0, 0); __builtin_amdgcn_s_setprio(0); } while (0)
; #define PG8_WAIT_V(n) asm volatile("s_waitcnt vmcnt(" #n ")" ::: "memory")
; #define PG8_WAIT_L(n) asm volatile("s_waitcnt lgkmcnt(" #n ")" ::: "memory")
; #define PG8_BAR __builtin_amdgcn_s_barrier()
; #define PG8_SCHED __builtin_amdgcn_sched_barrier(0)
; template <class Epi, class Sched, bool HALFN = false>
; __device__ __forceinline__ void gemm_phase(LAS unsigned char* lds, const Gemm g, const Sched& S, const Epi& E, int wave_s) {
;     ...
;         for (int t = 0; t < nt; t += 2) {
;             const bool last = (t == nt - 2);
;             const char* a1 = cA + (size_t)(t + 1) * kstep;
;             const char* a2 = last ? nA : cA + (size_t)(t + 2) * kstep; const char* b2 = last ? nB : cB + (size_t)(t + 2) * kstep;
;             const char* a3 = a2 + kstep; const char* b3 = b2 + kstep;
;             PG8_LDB(B0, 0, 0); if (!HALFN) PG8_LDB(B1, 0, 1); PG8_SCHED; PG8_LDA(At, 0, 0); PG8_STAGE(PG8_SA(1, 1), a1 + hstep, voffA);
;             PG8_WAIT_V(8); PG8_WAIT_L(0); PG8_BAR; PG8_MMA(0, 0, At, B0); if (!HALFN) PG8_MMA(0, 1, At, B1); PG8_BAR; PG8_SCHED;
;             PG8_LDA(At, 0, 1); PG8_STAGE(PG8_SB(0, 0), b2, voffB); PG8_STAGE(PG8_SB(0, 1), b2 + bh1, voffB); PG8_STAGE(PG8_SA(0, 0), a2, voffA);
.LBB0_515:
	s_add_u32 s35, s26, s34
	s_addc_u32 s46, s27, 0
	s_add_u32 s38, s35, 0x100
	s_addc_u32 s39, s46, 0
	s_and_b64 s[36:37], s[30:31], exec
	s_cselect_b32 s37, s17, s39
	s_cselect_b32 s36, s80, s38
	s_add_u32 s34, s24, s34
	s_addc_u32 s38, s25, 0
	s_add_u32 s34, s34, 0x100
	s_addc_u32 s38, s38, 0
	s_add_i32 s90, 0, 0x10000
	s_and_b64 s[30:31], s[30:31], exec
	s_cselect_b32 s39, s15, s38
	s_cselect_b32 s38, s81, s34
	s_add_i32 s31, 0, 0x14000
	s_add_u32 s56, s35, 0x10080
	s_addc_u32 s57, s46, 0
	s_add_i32 s89, s90, s52
	s_add_i32 m0, s23, 0xc000
	s_add_i32 s92, s23, 0xe000
	s_add_i32 s86, s89, 0x2000
	v_add_u32_e32 v139, s90, v1
	s_add_u32 s46, s38, 0x10000
	ds_read_b128 v[140:143], v139
	ds_read_b128 v[144:147], v139 offset:1024
	ds_read_b128 v[148:151], v139 offset:2048
	ds_read_b128 v[152:155], v139 offset:3072
	v_add_u32_e32 v139, s31, v1
	s_addc_u32 s47, s39, 0
	s_add_i32 s88, s31, s52
	ds_read_b128 v[156:159], v139
	ds_read_b128 v[160:163], v139 offset:1024
	ds_read_b128 v[164:167], v139 offset:2048
	ds_read_b128 v[168:171], v139 offset:3072
	s_add_i32 s87, s88, 0x2000
	s_add_i32 s85, 0, 0x18000
	s_add_i32 s84, 0, 0x1c000
	s_add_u32 s34, s36, 0x10000
	s_addc_u32 s35, s37, 0
	s_add_i32 s83, s85, s52
	s_add_i32 s82, s83, 0x2000
	s_add_u32 s30, s38, 0x10080
	s_addc_u32 s31, s39, 0
	s_add_i32 s91, s84, s52
	s_add_i32 s90, s91, 0x2000
	v_lshl_add_u64 v[196:197], s[56:57], 0, v[132:133]
	ds_read_b128 v[172:175], v138
	ds_read_b128 v[176:179], v138 offset:1024
	ds_read_b128 v[180:183], v138 offset:2048
	ds_read_b128 v[184:187], v138 offset:3072
	ds_read_b128 v[188:191], v138 offset:4096
	ds_read_b128 v[192:195], v138 offset:5120
	ds_read_b128 v[208:211], v138 offset:6144
	ds_read_b128 v[212:215], v138 offset:7168
	global_load_lds_dwordx4 v[196:197], off
	v_lshl_add_u64 v[196:197], s[56:57], 0, v[134:135]
	s_mov_b32 m0, s92
	s_nop 0
	global_load_lds_dwordx4 v[196:197], off
	s_waitcnt vmcnt(8)
	s_waitcnt lgkmcnt(0)
	s_barrier
	s_setprio 1
	v_mfma_f32_16x16x32_bf16 v[128:131], v[140:143], v[172:175], v[128:131]
	v_mfma_f32_16x16x32_bf16 v[124:127], v[148:151], v[172:175], v[124:127]
	v_mfma_f32_16x16x32_bf16 v[120:123], v[140:143], v[180:183], v[120:123]
	v_mfma_f32_16x16x32_bf16 v[112:115], v[148:151], v[180:183], v[112:115]
	v_mfma_f32_16x16x32_bf16 v[104:107], v[140:143], v[188:191], v[104:107]
	v_mfma_f32_16x16x32_bf16 v[96:99], v[148:151], v[188:191], v[96:99]
	v_mfma_f32_16x16x32_bf16 v[88:91], v[140:143], v[208:211], v[88:91]
	v_mfma_f32_16x16x32_bf16 v[80:83], v[148:151], v[208:211], v[80:83]
	v_mfma_f32_16x16x32_bf16 v[128:131], v[144:147], v[176:179], v[128:131]
	v_mfma_f32_16x16x32_bf16 v[124:127], v[152:155], v[176:179], v[124:127]
	v_mfma_f32_16x16x32_bf16 v[120:123], v[144:147], v[184:187], v[120:123]
	v_mfma_f32_16x16x32_bf16 v[112:115], v[152:155], v[184:187], v[112:115]
	v_mfma_f32_16x16x32_bf16 v[104:107], v[144:147], v[192:195], v[104:107]
	v_mfma_f32_16x16x32_bf16 v[96:99], v[152:155], v[192:195], v[96:99]
	v_mfma_f32_16x16x32_bf16 v[88:91], v[144:147], v[212:215], v[88:91]
	v_mfma_f32_16x16x32_bf16 v[80:83], v[152:155], v[212:215], v[80:83]
	s_setprio 0
	s_setprio 1
	v_mfma_f32_16x16x32_bf16 v[116:119], v[156:159], v[172:175], v[116:119]
	v_mfma_f32_16x16x32_bf16 v[108:111], v[164:167], v[172:175], v[108:111]
	v_mfma_f32_16x16x32_bf16 v[100:103], v[156:159], v[180:183], v[100:103]
	v_mfma_f32_16x16x32_bf16 v[92:95], v[164:167], v[180:183], v[92:95]
	v_mfma_f32_16x16x32_bf16 v[84:87], v[156:159], v[188:191], v[84:87]
	v_mfma_f32_16x16x32_bf16 v[76:79], v[164:167], v[188:191], v[76:79]
	v_mfma_f32_16x16x32_bf16 v[72:75], v[156:159], v[208:211], v[72:75]
	v_mfma_f32_16x16x32_bf16 v[68:71], v[164:167], v[208:211], v[68:71]
	v_mfma_f32_16x16x32_bf16 v[116:119], v[160:163], v[176:179], v[116:119]
	v_mfma_f32_16x16x32_bf16 v[108:111], v[168:171], v[176:179], v[108:111]
	v_mfma_f32_16x16x32_bf16 v[100:103], v[160:163], v[184:187], v[100:103]
	v_mfma_f32_16x16x32_bf16 v[92:95], v[168:171], v[184:187], v[92:95]
	v_mfma_f32_16x16x32_bf16 v[84:87], v[160:163], v[192:195], v[84:87]
	v_mfma_f32_16x16x32_bf16 v[76:79], v[168:171], v[192:195], v[76:79]
	v_mfma_f32_16x16x32_bf16 v[72:75], v[160:163], v[212:215], v[72:75]
	v_mfma_f32_16x16x32_bf16 v[68:71], v[168:171], v[212:215], v[68:71]
	s_setprio 0
	s_barrier
	s_mov_b32 m0, s89
	v_lshl_add_u64 v[196:197], s[38:39], 0, v[18:19]
	ds_read_b128 v[172:175], v138 offset:16384
	ds_read_b128 v[176:179], v138 offset:17408
	ds_read_b128 v[180:183], v138 offset:18432
	ds_read_b128 v[184:187], v138 offset:19456
	ds_read_b128 v[188:191], v138 offset:20480
	ds_read_b128 v[192:195], v138 offset:21504
	ds_read_b128 v[208:211], v138 offset:22528
	ds_read_b128 v[212:215], v138 offset:23552
	global_load_lds_dwordx4 v[196:197], off
	v_lshl_add_u64 v[216:217], s[38:39], 0, v[136:137]
	s_mov_b32 m0, s86
	v_lshl_add_u64 v[218:219], s[46:47], 0, v[18:19]
	global_load_lds_dwordx4 v[216:217], off
	s_mov_b32 m0, s88
	v_lshl_add_u64 v[220:221], s[36:37], 0, v[134:135]
	global_load_lds_dwordx4 v[218:219], off
	v_lshl_add_u64 v[218:219], s[46:47], 0, v[136:137]
	s_mov_b32 m0, s87
	s_nop 0
	global_load_lds_dwordx4 v[218:219], off
	v_lshl_add_u64 v[218:219], s[36:37], 0, v[132:133]
	s_mov_b32 m0, s23
	s_nop 0
	global_load_lds_dwordx4 v[218:219], off
	s_mov_b32 m0, s62
	s_nop 0
	global_load_lds_dwordx4 v[220:221], off
	s_waitcnt vmcnt(8)
	s_waitcnt lgkmcnt(0)
	s_barrier
; #define PG8_STAGE(bufoff, gbase, voff) do { _Pragma("unroll") for (int _i = 0; _i < 2; ++_i) \
;         __builtin_amdgcn_global_load_lds((const unsigned*)((const char*)(gbase) + (voff)[_i]), (LAS unsigned*)(lds + (bufoff) + ldsw + _i * 8192), 16, 0, 0); } while (0)
; #define PG8_LDA(dst, b, h) do { _Pragma("unroll") for (int m = 0; m < 4; ++m) _Pragma("unroll") for (int k = 0; k < 2; ++k) dst[m][k] = *(const LAS bf16x8*)(lds + PG8_SA(b, h) + aoff + m * 2048 + k * 1024); } while (0)
; #define PG8_LDB(dst, b, h) do { _Pragma("unroll") for (int n = 0; n < 2; ++n) _Pragma("unroll") for (int k = 0; k < 2; ++k) dst[n][k] = *(const LAS bf16x8*)(lds + PG8_SB(b, h) + boff + n * 2048 + k * 1024); } while (0)
; #define PG8_MMA(ai, bj, At, Bt) do { __builtin_amdgcn_s_setprio(1); _Pragma("unroll") for (int m = 0; m < 4; ++m) _Pragma("unroll") for (int n = 0; n < 2; ++n) _Pragma("unroll") for (int k = 0; k < 2; ++k) \
;         acc[ai][bj][m][n] = __builtin_amdgcn_mfma_f32_16x16x32_bf16(Bt[n][k], At[m][k], acc[ai][bj][m][n], 0, 0, 0); __builtin_amdgcn_s_setprio(0); } while (0)
; #define PG8_WAIT_V(n) asm volatile("s_waitcnt vmcnt(" #n ")" ::: "memory")
; #define PG8_WAIT_L(n) asm volatile("s_waitcnt lgkmcnt(" #n ")" ::: "memory")
; #define PG8_BAR __builtin_amdgcn_s_barrier()
; #define PG8_SCHED __builtin_amdgcn_sched_barrier(0)
; template <class Epi, class Sched, bool HALFN = false>
; __device__ __forceinline__ void gemm_phase(LAS unsigned char* lds, const Gemm g, const Sched& S, const Epi& E, int wave_s) {
;     ...
;             PG8_WAIT_V(8); PG8_WAIT_L(0); PG8_BAR; PG8_MMA(1, 0, At, B0); if (!HALFN) PG8_MMA(1, 1, At, B1); PG8_BAR; PG8_SCHED;
;             PG8_LDB(B0, 1, 0); if (!HALFN) PG8_LDB(B1, 1, 1); PG8_SCHED; PG8_LDA(At, 1, 0); PG8_STAGE(PG8_SA(0, 1), a2 + hstep, voffA);
;             PG8_WAIT_V(8); PG8_WAIT_L(0); PG8_BAR; PG8_MMA(0, 0, At, B0); if (!HALFN) PG8_MMA(0, 1, At, B1); PG8_BAR; PG8_SCHED;
	s_setprio 1
	v_mfma_f32_16x16x32_bf16 v[64:67], v[140:143], v[172:175], v[64:67]
	v_mfma_f32_16x16x32_bf16 v[60:63], v[148:151], v[172:175], v[60:63]
	v_mfma_f32_16x16x32_bf16 v[56:59], v[140:143], v[180:183], v[56:59]
	v_mfma_f32_16x16x32_bf16 v[48:51], v[148:151], v[180:183], v[48:51]
	v_mfma_f32_16x16x32_bf16 v[40:43], v[140:143], v[188:191], v[40:43]
	v_mfma_f32_16x16x32_bf16 v[32:35], v[148:151], v[188:191], v[32:35]
	v_mfma_f32_16x16x32_bf16 v[24:27], v[140:143], v[208:211], v[24:27]
	v_mfma_f32_16x16x32_bf16 v[14:17], v[148:151], v[208:211], v[14:17]
	v_mfma_f32_16x16x32_bf16 v[64:67], v[144:147], v[176:179], v[64:67]
	v_mfma_f32_16x16x32_bf16 v[60:63], v[152:155], v[176:179], v[60:63]
	v_mfma_f32_16x16x32_bf16 v[56:59], v[144:147], v[184:187], v[56:59]
	v_mfma_f32_16x16x32_bf16 v[48:51], v[152:155], v[184:187], v[48:51]
	v_mfma_f32_16x16x32_bf16 v[40:43], v[144:147], v[192:195], v[40:43]
	v_mfma_f32_16x16x32_bf16 v[32:35], v[152:155], v[192:195], v[32:35]
	v_mfma_f32_16x16x32_bf16 v[24:27], v[144:147], v[212:215], v[24:27]
	v_mfma_f32_16x16x32_bf16 v[14:17], v[152:155], v[212:215], v[14:17]
	s_setprio 0
	s_setprio 1
	v_mfma_f32_16x16x32_bf16 v[52:55], v[156:159], v[172:175], v[52:55]
	v_mfma_f32_16x16x32_bf16 v[44:47], v[164:167], v[172:175], v[44:47]
	v_mfma_f32_16x16x32_bf16 v[36:39], v[156:159], v[180:183], v[36:39]
	v_mfma_f32_16x16x32_bf16 v[28:31], v[164:167], v[180:183], v[28:31]
	v_mfma_f32_16x16x32_bf16 v[20:23], v[156:159], v[188:191], v[20:23]
	v_mfma_f32_16x16x32_bf16 v[10:13], v[164:167], v[188:191], v[10:13]
	v_mfma_f32_16x16x32_bf16 v[6:9], v[156:159], v[208:211], v[6:9]
	v_mfma_f32_16x16x32_bf16 v[2:5], v[164:167], v[208:211], v[2:5]
	v_mfma_f32_16x16x32_bf16 v[52:55], v[160:163], v[176:179], v[52:55]
	v_mfma_f32_16x16x32_bf16 v[44:47], v[168:171], v[176:179], v[44:47]
	v_mfma_f32_16x16x32_bf16 v[36:39], v[160:163], v[184:187], v[36:39]
	v_mfma_f32_16x16x32_bf16 v[28:31], v[168:171], v[184:187], v[28:31]
	v_mfma_f32_16x16x32_bf16 v[20:23], v[160:163], v[192:195], v[20:23]
	v_mfma_f32_16x16x32_bf16 v[10:13], v[168:171], v[192:195], v[10:13]
	v_mfma_f32_16x16x32_bf16 v[6:9], v[160:163], v[212:215], v[6:9]
	v_mfma_f32_16x16x32_bf16 v[2:5], v[168:171], v[212:215], v[2:5]
	s_setprio 0
	s_barrier
	v_add_u32_e32 v139, s85, v1
	ds_read_b128 v[140:143], v139
	ds_read_b128 v[144:147], v139 offset:1024
	ds_read_b128 v[148:151], v139 offset:2048
	ds_read_b128 v[152:155], v139 offset:3072
	v_add_u32_e32 v139, s84, v1
	ds_read_b128 v[156:159], v139
	ds_read_b128 v[160:163], v139 offset:1024
	ds_read_b128 v[164:167], v139 offset:2048
	ds_read_b128 v[168:171], v139 offset:3072
	s_mov_b32 m0, s64
	v_lshl_add_u64 v[222:223], s[34:35], 0, v[132:133]
	ds_read_b128 v[172:175], v138 offset:32768
	ds_read_b128 v[176:179], v138 offset:33792
	ds_read_b128 v[180:183], v138 offset:34816
	ds_read_b128 v[184:187], v138 offset:35840
	ds_read_b128 v[188:191], v138 offset:36864
	ds_read_b128 v[192:195], v138 offset:37888
	ds_read_b128 v[208:211], v138 offset:38912
	ds_read_b128 v[212:215], v138 offset:39936
	global_load_lds_dwordx4 v[222:223], off
	v_lshl_add_u64 v[222:223], s[34:35], 0, v[134:135]
	s_mov_b32 m0, s65
	s_nop 0
	global_load_lds_dwordx4 v[222:223], off
	s_waitcnt vmcnt(8)
	s_waitcnt lgkmcnt(0)
	s_barrier
	s_setprio 1
	v_mfma_f32_16x16x32_bf16 v[128:131], v[140:143], v[172:175], v[128:131]
	v_mfma_f32_16x16x32_bf16 v[124:127], v[148:151], v[172:175], v[124:127]
	v_mfma_f32_16x16x32_bf16 v[120:123], v[140:143], v[180:183], v[120:123]
	v_mfma_f32_16x16x32_bf16 v[112:115], v[148:151], v[180:183], v[112:115]
	v_mfma_f32_16x16x32_bf16 v[104:107], v[140:143], v[188:191], v[104:107]
	v_mfma_f32_16x16x32_bf16 v[96:99], v[148:151], v[188:191], v[96:99]
	v_mfma_f32_16x16x32_bf16 v[88:91], v[140:143], v[208:211], v[88:91]
	v_mfma_f32_16x16x32_bf16 v[80:83], v[148:151], v[208:211], v[80:83]
	v_mfma_f32_16x16x32_bf16 v[128:131], v[144:147], v[176:179], v[128:131]
	v_mfma_f32_16x16x32_bf16 v[124:127], v[152:155], v[176:179], v[124:127]
	v_mfma_f32_16x16x32_bf16 v[120:123], v[144:147], v[184:187], v[120:123]
	v_mfma_f32_16x16x32_bf16 v[112:115], v[152:155], v[184:187], v[112:115]
	v_mfma_f32_16x16x32_bf16 v[104:107], v[144:147], v[192:195], v[104:107]
	v_mfma_f32_16x16x32_bf16 v[96:99], v[152:155], v[192:195], v[96:99]
	v_mfma_f32_16x16x32_bf16 v[88:91], v[144:147], v[212:215], v[88:91]
	v_mfma_f32_16x16x32_bf16 v[80:83], v[152:155], v[212:215], v[80:83]
	s_setprio 0
	s_setprio 1
	v_mfma_f32_16x16x32_bf16 v[116:119], v[156:159], v[172:175], v[116:119]
	v_mfma_f32_16x16x32_bf16 v[108:111], v[164:167], v[172:175], v[108:111]
	v_mfma_f32_16x16x32_bf16 v[100:103], v[156:159], v[180:183], v[100:103]
	v_mfma_f32_16x16x32_bf16 v[92:95], v[164:167], v[180:183], v[92:95]
	v_mfma_f32_16x16x32_bf16 v[84:87], v[156:159], v[188:191], v[84:87]
	v_mfma_f32_16x16x32_bf16 v[76:79], v[164:167], v[188:191], v[76:79]
	v_mfma_f32_16x16x32_bf16 v[72:75], v[156:159], v[208:211], v[72:75]
	v_mfma_f32_16x16x32_bf16 v[68:71], v[164:167], v[208:211], v[68:71]
	v_mfma_f32_16x16x32_bf16 v[116:119], v[160:163], v[176:179], v[116:119]
	v_mfma_f32_16x16x32_bf16 v[108:111], v[168:171], v[176:179], v[108:111]
	v_mfma_f32_16x16x32_bf16 v[100:103], v[160:163], v[184:187], v[100:103]
	v_mfma_f32_16x16x32_bf16 v[92:95], v[168:171], v[184:187], v[92:95]
	v_mfma_f32_16x16x32_bf16 v[84:87], v[160:163], v[192:195], v[84:87]
	v_mfma_f32_16x16x32_bf16 v[76:79], v[168:171], v[192:195], v[76:79]
	v_mfma_f32_16x16x32_bf16 v[72:75], v[160:163], v[212:215], v[72:75]
	v_mfma_f32_16x16x32_bf16 v[68:71], v[168:171], v[212:215], v[68:71]
	s_setprio 0
	s_barrier
; #define PG8_STAGE(bufoff, gbase, voff) do { _Pragma("unroll") for (int _i = 0; _i < 2; ++_i) \
;         __builtin_amdgcn_global_load_lds((const unsigned*)((const char*)(gbase) + (voff)[_i]), (LAS unsigned*)(lds + (bufoff) + ldsw + _i * 8192), 16, 0, 0); } while (0)
; #define PG8_LDA(dst, b, h) do { _Pragma("unroll") for (int m = 0; m < 4; ++m) _Pragma("unroll") for (int k = 0; k < 2; ++k) dst[m][k] = *(const LAS bf16x8*)(lds + PG8_SA(b, h) + aoff + m * 2048 + k * 1024); } while (0)
; #define PG8_MMA(ai, bj, At, Bt) do { __builtin_amdgcn_s_setprio(1); _Pragma("unroll") for (int m = 0; m < 4; ++m) _Pragma("unroll") for (int n = 0; n < 2; ++n) _Pragma("unroll") for (int k = 0; k < 2; ++k) \
;         acc[ai][bj][m][n] = __builtin_amdgcn_mfma_f32_16x16x32_bf16(Bt[n][k], At[m][k], acc[ai][bj][m][n], 0, 0, 0); __builtin_amdgcn_s_setprio(0); } while (0)
; #define PG8_WAIT_V(n) asm volatile("s_waitcnt vmcnt(" #n ")" ::: "memory")
; #define PG8_WAIT_L(n) asm volatile("s_waitcnt lgkmcnt(" #n ")" ::: "memory")
; #define PG8_BAR __builtin_amdgcn_s_barrier()
; #define PG8_SCHED __builtin_amdgcn_sched_barrier(0)
; template <class Epi, class Sched, bool HALFN = false>
; __device__ __forceinline__ void gemm_phase(LAS unsigned char* lds, const Gemm g, const Sched& S, const Epi& E, int wave_s) {
;     ...
;             PG8_LDA(At, 1, 1); PG8_STAGE(PG8_SB(1, 0), b3, voffB); PG8_STAGE(PG8_SB(1, 1), b3 + bh1, voffB); PG8_STAGE(PG8_SA(1, 0), a3, voffA);
;             PG8_WAIT_V(8); PG8_WAIT_L(0); PG8_BAR; PG8_MMA(1, 0, At, B0); if (!HALFN) PG8_MMA(1, 1, At, B1); PG8_BAR; PG8_SCHED;
;         }
;         if (wr == 0) PG8_BAR;
	s_mov_b32 m0, s83
	v_lshl_add_u64 v[196:197], v[196:197], 0, s[50:51]
	ds_read_b128 v[172:175], v138 offset:49152
	ds_read_b128 v[176:179], v138 offset:50176
	ds_read_b128 v[180:183], v138 offset:51200
	ds_read_b128 v[184:187], v138 offset:52224
	ds_read_b128 v[188:191], v138 offset:53248
	ds_read_b128 v[192:195], v138 offset:54272
	ds_read_b128 v[208:211], v138 offset:55296
	ds_read_b128 v[212:215], v138 offset:56320
	global_load_lds_dwordx4 v[196:197], off
	v_lshl_add_u64 v[196:197], v[216:217], 0, s[50:51]
	s_mov_b32 m0, s82
	s_nop 0
	global_load_lds_dwordx4 v[196:197], off
	v_lshl_add_u64 v[196:197], s[30:31], 0, v[18:19]
	s_mov_b32 m0, s91
	s_nop 0
	global_load_lds_dwordx4 v[196:197], off
	v_lshl_add_u64 v[196:197], s[30:31], 0, v[136:137]
	s_mov_b32 m0, s90
	s_nop 0
	global_load_lds_dwordx4 v[196:197], off
	v_lshl_add_u64 v[196:197], v[218:219], 0, s[50:51]
	s_mov_b32 m0, s66
	s_nop 0
	global_load_lds_dwordx4 v[196:197], off
	v_lshl_add_u64 v[196:197], v[220:221], 0, s[50:51]
	s_mov_b32 m0, s67
	s_nop 0
	global_load_lds_dwordx4 v[196:197], off
	s_waitcnt vmcnt(8)
	s_waitcnt lgkmcnt(0)
	s_barrier
	s_setprio 1
	v_mfma_f32_16x16x32_bf16 v[64:67], v[140:143], v[172:175], v[64:67]
	v_mfma_f32_16x16x32_bf16 v[60:63], v[148:151], v[172:175], v[60:63]
	v_mfma_f32_16x16x32_bf16 v[56:59], v[140:143], v[180:183], v[56:59]
	v_mfma_f32_16x16x32_bf16 v[48:51], v[148:151], v[180:183], v[48:51]
	v_mfma_f32_16x16x32_bf16 v[40:43], v[140:143], v[188:191], v[40:43]
	v_mfma_f32_16x16x32_bf16 v[32:35], v[148:151], v[188:191], v[32:35]
	v_mfma_f32_16x16x32_bf16 v[24:27], v[140:143], v[208:211], v[24:27]
	v_mfma_f32_16x16x32_bf16 v[14:17], v[148:151], v[208:211], v[14:17]
	v_mfma_f32_16x16x32_bf16 v[64:67], v[144:147], v[176:179], v[64:67]
	v_mfma_f32_16x16x32_bf16 v[60:63], v[152:155], v[176:179], v[60:63]
	v_mfma_f32_16x16x32_bf16 v[56:59], v[144:147], v[184:187], v[56:59]
	v_mfma_f32_16x16x32_bf16 v[48:51], v[152:155], v[184:187], v[48:51]
	v_mfma_f32_16x16x32_bf16 v[40:43], v[144:147], v[192:195], v[40:43]
	v_mfma_f32_16x16x32_bf16 v[32:35], v[152:155], v[192:195], v[32:35]
	v_mfma_f32_16x16x32_bf16 v[24:27], v[144:147], v[212:215], v[24:27]
	v_mfma_f32_16x16x32_bf16 v[14:17], v[152:155], v[212:215], v[14:17]
	s_setprio 0
	s_setprio 1
	v_mfma_f32_16x16x32_bf16 v[52:55], v[156:159], v[172:175], v[52:55]
	v_mfma_f32_16x16x32_bf16 v[44:47], v[164:167], v[172:175], v[44:47]
	v_mfma_f32_16x16x32_bf16 v[36:39], v[156:159], v[180:183], v[36:39]
	v_mfma_f32_16x16x32_bf16 v[28:31], v[164:167], v[180:183], v[28:31]
	v_mfma_f32_16x16x32_bf16 v[20:23], v[156:159], v[188:191], v[20:23]
	v_mfma_f32_16x16x32_bf16 v[10:13], v[164:167], v[188:191], v[10:13]
	v_mfma_f32_16x16x32_bf16 v[6:9], v[156:159], v[208:211], v[6:9]
	v_mfma_f32_16x16x32_bf16 v[2:5], v[164:167], v[208:211], v[2:5]
	v_mfma_f32_16x16x32_bf16 v[52:55], v[160:163], v[176:179], v[52:55]
	v_mfma_f32_16x16x32_bf16 v[44:47], v[168:171], v[176:179], v[44:47]
	v_mfma_f32_16x16x32_bf16 v[36:39], v[160:163], v[184:187], v[36:39]
	v_mfma_f32_16x16x32_bf16 v[28:31], v[168:171], v[184:187], v[28:31]
	v_mfma_f32_16x16x32_bf16 v[20:23], v[160:163], v[192:195], v[20:23]
	v_mfma_f32_16x16x32_bf16 v[10:13], v[168:171], v[192:195], v[10:13]
	v_mfma_f32_16x16x32_bf16 v[6:9], v[160:163], v[212:215], v[6:9]
	v_mfma_f32_16x16x32_bf16 v[2:5], v[168:171], v[212:215], v[2:5]
	s_setprio 0
	s_barrier
	s_movk_i32 s34, 0x100
	s_andn2_b64 vcc, exec, s[28:29]
	s_mov_b64 s[30:31], -1
	s_mov_b64 s[28:29], 0
	s_cbranch_vccz .LBB0_515
	s_and_b64 vcc, exec, s[12:13]
	s_cbranch_vccz .LBB0_518
	s_barrier

; #define PG8_STAGE(bufoff, gbase, voff) do { _Pragma("unroll") for (int _i = 0; _i < 2; ++_i) \
;         __builtin_amdgcn_global_load_lds((const unsigned*)((const char*)(gbase) + (voff)[_i]), (LAS unsigned*)(lds + (bufoff) + ldsw + _i * 8192), 16, 0, 0); } while (0)
; #define PG8_LDA(dst, b, h) do { _Pragma("unroll") for (int m = 0; m < 4; ++m) _Pragma("unroll") for (int k = 0; k < 2; ++k) dst[m][k] = *(const LAS bf16x8*)(lds + PG8_SA(b, h) + aoff + m * 2048 + k * 1024); } while (0)
; #define PG8_LDB(dst, b, h) do { _Pragma("unroll") for (int n = 0; n < 2; ++n) _Pragma("unroll") for (int k = 0; k < 2; ++k) dst[n][k] = *(const LAS bf16x8*)(lds + PG8_SB(b, h) + boff + n * 2048 + k * 1024); } while (0)
; #define PG8_MMA(ai, bj, At, Bt) do { __builtin_amdgcn_s_setprio(1); _Pragma("unroll") for (int m = 0; m < 4; ++m) _Pragma("unroll") for (int n = 0; n < 2; ++n) _Pragma("unroll") for (int k = 0; k < 2; ++k) \
;         acc[ai][bj][m][n] = __builtin_amdgcn_mfma_f32_16x16x32_bf16(Bt[n][k], At[m][k], acc[ai][bj][m][n], 0, 0, 0); __builtin_amdgcn_s_setprio(0); } while (0)
; #define PG8_WAIT_V(n) asm volatile("s_waitcnt vmcnt(" #n ")" ::: "memory")
; #define PG8_BAR __builtin_amdgcn_s_barrier()
; template <class Epi, class Sched, bool HALFN = false>
; __device__ __forceinline__ void gemm_phase(LAS unsigned char* lds, const Gemm g, const Sched& S, const Epi& E, int wave_s) {
;     ...
;         const char* nA = has_next ? (const char*)g.A + (size_t)nxt.z * g.zA * 2 + (size_t)nxt.pm * tstep : cA; const char* nB = has_next ? (const char*)g.Bt + (size_t)nxt.z * g.zB * 2 + (size_t)nxt.pn * (HALFN ? hstep : tstep) : cB;
;         for (int t = 0; t < nt; t += 2) {
;             const bool last = (t == nt - 2);
;             const char* a1 = cA + (size_t)(t + 1) * kstep;
;             const char* a2 = last ? nA : cA + (size_t)(t + 2) * kstep; const char* b2 = last ? nB : cB + (size_t)(t + 2) * kstep;
;             const char* a3 = a2 + kstep; const char* b3 = b2 + kstep;
;             PG8_LDB(B0, 0, 0); if (!HALFN) PG8_LDB(B1, 0, 1); PG8_SCHED; PG8_LDA(At, 0, 0); PG8_STAGE(PG8_SA(1, 1), a1 + hstep, voffA);
;             PG8_WAIT_V(8); PG8_WAIT_L(0); PG8_BAR; PG8_MMA(0, 0, At, B0); if (!HALFN) PG8_MMA(0, 1, At, B1); PG8_BAR; PG8_SCHED;
;             PG8_LDA(At, 0, 1); PG8_STAGE(PG8_SB(0, 0), b2, voffB); PG8_STAGE(PG8_SB(0, 1), b2 + bh1, voffB); PG8_STAGE(PG8_SA(0, 0), a2, voffA);
.LBB0_576:
	s_ashr_i32 s21, s20, 31
	s_lshl_b64 s[22:23], s[20:21], 16
	s_add_u32 s22, s36, s22
	s_addc_u32 s23, s37, s23
	s_and_b64 s[24:25], s[4:5], exec
	s_cselect_b32 s35, s23, s31
	s_cselect_b32 s34, s22, s30
	s_ashr_i32 s19, s18, 31
	s_lshl_b64 s[24:25], s[18:19], 16
	s_add_u32 s24, s38, s24
	s_addc_u32 s25, s39, s25
	s_and_b64 s[64:65], s[4:5], exec
	s_cselect_b32 s29, s25, s29
	s_cselect_b32 s28, s24, s28
	s_add_i32 s19, 0, 0x10000
	s_add_i32 s21, 0, 0x14000
	v_add_u32_e32 v14, s19, v1
	v_add_u32_e32 v32, s21, v1
	ds_read_b128 v[2:5], v14
	ds_read_b128 v[6:9], v14 offset:1024
	ds_read_b128 v[10:13], v14 offset:2048
	ds_read_b128 v[14:17], v14 offset:3072
	ds_read_b128 v[20:23], v32
	ds_read_b128 v[24:27], v32 offset:1024
	ds_read_b128 v[28:31], v32 offset:2048
	ds_read_b128 v[32:35], v32 offset:3072
	s_add_u32 s30, s30, 0x8080
	s_addc_u32 s31, s31, 0
	v_lshl_add_u64 v[68:69], s[30:31], 0, v[132:133]
	s_add_i32 m0, s27, 0xc000
	ds_read_b128 v[36:39], v138
	ds_read_b128 v[40:43], v138 offset:1024
	ds_read_b128 v[44:47], v138 offset:2048
	ds_read_b128 v[48:51], v138 offset:3072
	ds_read_b128 v[52:55], v138 offset:4096
	ds_read_b128 v[56:59], v138 offset:5120
	ds_read_b128 v[60:63], v138 offset:6144
	ds_read_b128 v[64:67], v138 offset:7168
	global_load_lds_dwordx4 v[68:69], off
	v_lshl_add_u64 v[68:69], s[30:31], 0, v[134:135]
	s_add_i32 m0, s27, 0xe000
	s_nop 0
	global_load_lds_dwordx4 v[68:69], off
	s_waitcnt vmcnt(8)
	s_waitcnt lgkmcnt(0)
	s_barrier
	s_setprio 1
	v_mfma_f32_16x16x32_bf16 v[68:71], v[2:5], v[36:39], 0
	v_mfma_f32_16x16x32_bf16 v[72:75], v[10:13], v[36:39], 0
	v_mfma_f32_16x16x32_bf16 v[76:79], v[2:5], v[44:47], 0
	v_mfma_f32_16x16x32_bf16 v[80:83], v[10:13], v[44:47], 0
	v_mfma_f32_16x16x32_bf16 v[84:87], v[2:5], v[52:55], 0
	v_mfma_f32_16x16x32_bf16 v[88:91], v[10:13], v[52:55], 0
	v_mfma_f32_16x16x32_bf16 v[92:95], v[2:5], v[60:63], 0
	v_mfma_f32_16x16x32_bf16 v[96:99], v[10:13], v[60:63], 0
	v_mfma_f32_16x16x32_bf16 v[68:71], v[6:9], v[40:43], v[68:71]
	v_mfma_f32_16x16x32_bf16 v[72:75], v[14:17], v[40:43], v[72:75]
	v_mfma_f32_16x16x32_bf16 v[76:79], v[6:9], v[48:51], v[76:79]
	v_mfma_f32_16x16x32_bf16 v[80:83], v[14:17], v[48:51], v[80:83]
	v_mfma_f32_16x16x32_bf16 v[84:87], v[6:9], v[56:59], v[84:87]
	v_mfma_f32_16x16x32_bf16 v[88:91], v[14:17], v[56:59], v[88:91]
	v_mfma_f32_16x16x32_bf16 v[92:95], v[6:9], v[64:67], v[92:95]
	v_mfma_f32_16x16x32_bf16 v[100:103], v[14:17], v[64:67], v[96:99]
	s_setprio 0
	s_setprio 1
	v_mfma_f32_16x16x32_bf16 v[96:99], v[20:23], v[36:39], 0
	v_mfma_f32_16x16x32_bf16 v[36:39], v[28:31], v[36:39], 0
	v_mfma_f32_16x16x32_bf16 v[108:111], v[24:27], v[40:43], v[96:99]
	v_mfma_f32_16x16x32_bf16 v[36:39], v[32:35], v[40:43], v[36:39]
	v_mfma_f32_16x16x32_bf16 v[40:43], v[20:23], v[44:47], 0
	v_mfma_f32_16x16x32_bf16 v[44:47], v[28:31], v[44:47], 0
	v_mfma_f32_16x16x32_bf16 v[40:43], v[24:27], v[48:51], v[40:43]
	v_mfma_f32_16x16x32_bf16 v[44:47], v[32:35], v[48:51], v[44:47]
	v_mfma_f32_16x16x32_bf16 v[48:51], v[20:23], v[52:55], 0
	v_mfma_f32_16x16x32_bf16 v[52:55], v[28:31], v[52:55], 0
	v_mfma_f32_16x16x32_bf16 v[48:51], v[24:27], v[56:59], v[48:51]
	v_mfma_f32_16x16x32_bf16 v[52:55], v[32:35], v[56:59], v[52:55]
	v_mfma_f32_16x16x32_bf16 v[56:59], v[20:23], v[60:63], 0
	v_mfma_f32_16x16x32_bf16 v[140:143], v[24:27], v[64:67], v[56:59]
	v_mfma_f32_16x16x32_bf16 v[56:59], v[28:31], v[60:63], 0
	v_mfma_f32_16x16x32_bf16 v[144:147], v[32:35], v[64:67], v[56:59]
	s_setprio 0
	s_barrier
	s_add_i32 s19, s19, s3
	v_lshl_add_u64 v[196:197], s[28:29], 0, v[18:19]
	s_mov_b32 m0, s19
	s_nop 1
	ds_read_b128 v[56:59], v138 offset:16384
	ds_read_b128 v[60:63], v138 offset:17408
	ds_read_b128 v[64:67], v138 offset:18432
	ds_read_b128 v[96:99], v138 offset:19456
	ds_read_b128 v[104:107], v138 offset:20480
	ds_read_b128 v[112:115], v138 offset:21504
	ds_read_b128 v[116:119], v138 offset:22528
	ds_read_b128 v[120:123], v138 offset:23552
	global_load_lds_dwordx4 v[196:197], off
	s_add_i32 m0, s19, 0x2000
	s_add_u32 s30, s28, 0x8000
	v_lshl_add_u64 v[252:253], s[28:29], 0, v[136:137]
	s_addc_u32 s31, s29, 0
	s_add_i32 s19, s21, s3
	global_load_lds_dwordx4 v[252:253], off
	v_lshl_add_u64 v[124:125], s[30:31], 0, v[18:19]
	s_mov_b32 m0, s19
	v_lshl_add_u64 v[202:203], s[34:35], 0, v[132:133]
	global_load_lds_dwordx4 v[124:125], off
	v_lshl_add_u64 v[124:125], s[30:31], 0, v[136:137]
	s_add_i32 m0, s19, 0x2000
	v_lshl_add_u64 v[198:199], s[34:35], 0, v[134:135]
	global_load_lds_dwordx4 v[124:125], off
	s_mov_b32 m0, s27
	s_nop 0
	global_load_lds_dwordx4 v[202:203], off
	s_mov_b32 m0, s41
	s_nop 0
	global_load_lds_dwordx4 v[198:199], off
	s_waitcnt vmcnt(8)
	s_waitcnt lgkmcnt(0)
	s_barrier
; #define PG8_STAGE(bufoff, gbase, voff) do { _Pragma("unroll") for (int _i = 0; _i < 2; ++_i) \
;         __builtin_amdgcn_global_load_lds((const unsigned*)((const char*)(gbase) + (voff)[_i]), (LAS unsigned*)(lds + (bufoff) + ldsw + _i * 8192), 16, 0, 0); } while (0)
; #define PG8_LDA(dst, b, h) do { _Pragma("unroll") for (int m = 0; m < 4; ++m) _Pragma("unroll") for (int k = 0; k < 2; ++k) dst[m][k] = *(const LAS bf16x8*)(lds + PG8_SA(b, h) + aoff + m * 2048 + k * 1024); } while (0)
; #define PG8_LDB(dst, b, h) do { _Pragma("unroll") for (int n = 0; n < 2; ++n) _Pragma("unroll") for (int k = 0; k < 2; ++k) dst[n][k] = *(const LAS bf16x8*)(lds + PG8_SB(b, h) + boff + n * 2048 + k * 1024); } while (0)
; #define PG8_MMA(ai, bj, At, Bt) do { __builtin_amdgcn_s_setprio(1); _Pragma("unroll") for (int m = 0; m < 4; ++m) _Pragma("unroll") for (int n = 0; n < 2; ++n) _Pragma("unroll") for (int k = 0; k < 2; ++k) \
;         acc[ai][bj][m][n] = __builtin_amdgcn_mfma_f32_16x16x32_bf16(Bt[n][k], At[m][k], acc[ai][bj][m][n], 0, 0, 0); __builtin_amdgcn_s_setprio(0); } while (0)
; #define PG8_WAIT_V(n) asm volatile("s_waitcnt vmcnt(" #n ")" ::: "memory")
; #define PG8_WAIT_L(n) asm volatile("s_waitcnt lgkmcnt(" #n ")" ::: "memory")
; #define PG8_BAR __builtin_amdgcn_s_barrier()
; #define PG8_SCHED __builtin_amdgcn_sched_barrier(0)
; template <class Epi, class Sched, bool HALFN = false>
; __device__ __forceinline__ void gemm_phase(LAS unsigned char* lds, const Gemm g, const Sched& S, const Epi& E, int wave_s) {
;     ...
;             PG8_WAIT_V(8); PG8_WAIT_L(0); PG8_BAR; PG8_MMA(1, 0, At, B0); if (!HALFN) PG8_MMA(1, 1, At, B1); PG8_BAR; PG8_SCHED;
;             PG8_LDB(B0, 1, 0); if (!HALFN) PG8_LDB(B1, 1, 1); PG8_SCHED; PG8_LDA(At, 1, 0); PG8_STAGE(PG8_SA(0, 1), a2 + hstep, voffA);
;             PG8_WAIT_V(8); PG8_WAIT_L(0); PG8_BAR; PG8_MMA(0, 0, At, B0); if (!HALFN) PG8_MMA(0, 1, At, B1); PG8_BAR; PG8_SCHED;
	s_setprio 1
	v_mfma_f32_16x16x32_bf16 v[124:127], v[2:5], v[56:59], 0
	v_mfma_f32_16x16x32_bf16 v[148:151], v[6:9], v[60:63], v[124:127]
	v_mfma_f32_16x16x32_bf16 v[124:127], v[10:13], v[56:59], 0
	v_mfma_f32_16x16x32_bf16 v[152:155], v[14:17], v[60:63], v[124:127]
	v_mfma_f32_16x16x32_bf16 v[124:127], v[2:5], v[64:67], 0
	v_mfma_f32_16x16x32_bf16 v[156:159], v[6:9], v[96:99], v[124:127]
	v_mfma_f32_16x16x32_bf16 v[124:127], v[10:13], v[64:67], 0
	v_mfma_f32_16x16x32_bf16 v[160:163], v[14:17], v[96:99], v[124:127]
	v_mfma_f32_16x16x32_bf16 v[124:127], v[2:5], v[104:107], 0
	v_mfma_f32_16x16x32_bf16 v[2:5], v[2:5], v[116:119], 0
	v_mfma_f32_16x16x32_bf16 v[164:167], v[6:9], v[112:115], v[124:127]
	v_mfma_f32_16x16x32_bf16 v[2:5], v[6:9], v[120:123], v[2:5]
	v_mfma_f32_16x16x32_bf16 v[6:9], v[10:13], v[116:119], 0
	v_mfma_f32_16x16x32_bf16 v[124:127], v[10:13], v[104:107], 0
	v_mfma_f32_16x16x32_bf16 v[6:9], v[14:17], v[120:123], v[6:9]
	v_mfma_f32_16x16x32_bf16 v[168:171], v[14:17], v[112:115], v[124:127]
	s_setprio 0
	s_setprio 1
	v_mfma_f32_16x16x32_bf16 v[14:17], v[28:31], v[56:59], 0
	v_mfma_f32_16x16x32_bf16 v[172:175], v[32:35], v[60:63], v[14:17]
	v_mfma_f32_16x16x32_bf16 v[14:17], v[20:23], v[64:67], 0
	v_mfma_f32_16x16x32_bf16 v[176:179], v[24:27], v[96:99], v[14:17]
	v_mfma_f32_16x16x32_bf16 v[14:17], v[28:31], v[64:67], 0
	v_mfma_f32_16x16x32_bf16 v[180:183], v[32:35], v[96:99], v[14:17]
	v_mfma_f32_16x16x32_bf16 v[14:17], v[20:23], v[104:107], 0
	v_mfma_f32_16x16x32_bf16 v[184:187], v[24:27], v[112:115], v[14:17]
	v_mfma_f32_16x16x32_bf16 v[14:17], v[28:31], v[104:107], 0
	v_mfma_f32_16x16x32_bf16 v[10:13], v[20:23], v[56:59], 0
	v_mfma_f32_16x16x32_bf16 v[188:191], v[32:35], v[112:115], v[14:17]
	v_mfma_f32_16x16x32_bf16 v[14:17], v[20:23], v[116:119], 0
	v_mfma_f32_16x16x32_bf16 v[10:13], v[24:27], v[60:63], v[10:13]
	v_mfma_f32_16x16x32_bf16 v[192:195], v[24:27], v[120:123], v[14:17]
	v_mfma_f32_16x16x32_bf16 v[14:17], v[28:31], v[116:119], 0
	v_mfma_f32_16x16x32_bf16 v[208:211], v[32:35], v[120:123], v[14:17]
	s_setprio 0
	s_barrier
	s_add_i32 s19, 0, 0x18000
	v_add_u32_e32 v24, s19, v1
	s_add_i32 s21, 0, 0x1c000
	s_nop 1
	ds_read_b128 v[14:17], v24
	ds_read_b128 v[20:23], v24 offset:1024
	ds_read_b128 v[28:31], v24 offset:2048
	ds_read_b128 v[212:215], v24 offset:3072
	v_add_u32_e32 v24, s21, v1
	ds_read_b128 v[216:219], v24
	ds_read_b128 v[220:223], v24 offset:1024
	ds_read_b128 v[224:227], v24 offset:2048
	ds_read_b128 v[228:231], v24 offset:3072
	s_add_u32 s30, s34, 0x8000
	s_addc_u32 s31, s35, 0
	s_mov_b32 m0, s42
	v_lshl_add_u64 v[56:57], s[30:31], 0, v[132:133]
	ds_read_b128 v[24:27], v138 offset:32768
	ds_read_b128 v[32:35], v138 offset:33792
	ds_read_b128 v[60:63], v138 offset:34816
	ds_read_b128 v[232:235], v138 offset:35840
	ds_read_b128 v[236:239], v138 offset:36864
	ds_read_b128 v[240:243], v138 offset:37888
	ds_read_b128 v[244:247], v138 offset:38912
	ds_read_b128 v[248:251], v138 offset:39936
	global_load_lds_dwordx4 v[56:57], off
	v_lshl_add_u64 v[56:57], s[30:31], 0, v[134:135]
	s_mov_b32 m0, s45
	s_nop 0
	global_load_lds_dwordx4 v[56:57], off
	s_waitcnt vmcnt(8)
	s_waitcnt lgkmcnt(0)
	s_barrier
	s_setprio 1
	v_mfma_f32_16x16x32_bf16 v[56:59], v[14:17], v[24:27], v[68:71]
	v_mfma_f32_16x16x32_bf16 v[128:131], v[20:23], v[32:35], v[56:59]
	v_mfma_f32_16x16x32_bf16 v[56:59], v[28:31], v[24:27], v[72:75]
	v_mfma_f32_16x16x32_bf16 v[124:127], v[212:215], v[32:35], v[56:59]
	v_mfma_f32_16x16x32_bf16 v[56:59], v[14:17], v[60:63], v[76:79]
	v_mfma_f32_16x16x32_bf16 v[112:115], v[20:23], v[232:235], v[56:59]
	v_mfma_f32_16x16x32_bf16 v[56:59], v[28:31], v[60:63], v[80:83]
	v_mfma_f32_16x16x32_bf16 v[104:107], v[212:215], v[232:235], v[56:59]
	v_mfma_f32_16x16x32_bf16 v[56:59], v[14:17], v[236:239], v[84:87]
	v_mfma_f32_16x16x32_bf16 v[96:99], v[20:23], v[240:243], v[56:59]
	v_mfma_f32_16x16x32_bf16 v[56:59], v[28:31], v[236:239], v[88:91]
	v_mfma_f32_16x16x32_bf16 v[88:91], v[212:215], v[240:243], v[56:59]
	v_mfma_f32_16x16x32_bf16 v[56:59], v[14:17], v[244:247], v[92:95]
	v_mfma_f32_16x16x32_bf16 v[64:67], v[20:23], v[248:251], v[56:59]
	v_mfma_f32_16x16x32_bf16 v[56:59], v[28:31], v[244:247], v[100:103]
	v_mfma_f32_16x16x32_bf16 v[56:59], v[212:215], v[248:251], v[56:59]
	s_setprio 0
	s_setprio 1
	v_mfma_f32_16x16x32_bf16 v[68:71], v[216:219], v[24:27], v[108:111]
	v_mfma_f32_16x16x32_bf16 v[24:27], v[224:227], v[24:27], v[36:39]
	v_mfma_f32_16x16x32_bf16 v[116:119], v[228:231], v[32:35], v[24:27]
	v_mfma_f32_16x16x32_bf16 v[24:27], v[216:219], v[60:63], v[40:43]
	v_mfma_f32_16x16x32_bf16 v[108:111], v[220:223], v[232:235], v[24:27]
	v_mfma_f32_16x16x32_bf16 v[24:27], v[224:227], v[60:63], v[44:47]
	v_mfma_f32_16x16x32_bf16 v[100:103], v[228:231], v[232:235], v[24:27]
	v_mfma_f32_16x16x32_bf16 v[24:27], v[216:219], v[236:239], v[48:51]
	v_mfma_f32_16x16x32_bf16 v[92:95], v[220:223], v[240:243], v[24:27]
	v_mfma_f32_16x16x32_bf16 v[24:27], v[224:227], v[236:239], v[52:55]
	v_mfma_f32_16x16x32_bf16 v[84:87], v[228:231], v[240:243], v[24:27]
	v_mfma_f32_16x16x32_bf16 v[24:27], v[216:219], v[244:247], v[140:143]
	v_mfma_f32_16x16x32_bf16 v[60:63], v[220:223], v[248:251], v[24:27]
	v_mfma_f32_16x16x32_bf16 v[24:27], v[224:227], v[244:247], v[144:147]
	v_mfma_f32_16x16x32_bf16 v[120:123], v[220:223], v[32:35], v[68:71]
	v_mfma_f32_16x16x32_bf16 v[52:55], v[228:231], v[248:251], v[24:27]
	s_setprio 0
	s_barrier
; #define PG8_STAGE(bufoff, gbase, voff) do { _Pragma("unroll") for (int _i = 0; _i < 2; ++_i) \
;         __builtin_amdgcn_global_load_lds((const unsigned*)((const char*)(gbase) + (voff)[_i]), (LAS unsigned*)(lds + (bufoff) + ldsw + _i * 8192), 16, 0, 0); } while (0)
; #define PG8_LDA(dst, b, h) do { _Pragma("unroll") for (int m = 0; m < 4; ++m) _Pragma("unroll") for (int k = 0; k < 2; ++k) dst[m][k] = *(const LAS bf16x8*)(lds + PG8_SA(b, h) + aoff + m * 2048 + k * 1024); } while (0)
; #define PG8_MMA(ai, bj, At, Bt) do { __builtin_amdgcn_s_setprio(1); _Pragma("unroll") for (int m = 0; m < 4; ++m) _Pragma("unroll") for (int n = 0; n < 2; ++n) _Pragma("unroll") for (int k = 0; k < 2; ++k) \
;         acc[ai][bj][m][n] = __builtin_amdgcn_mfma_f32_16x16x32_bf16(Bt[n][k], At[m][k], acc[ai][bj][m][n], 0, 0, 0); __builtin_amdgcn_s_setprio(0); } while (0)
; #define PG8_WAIT_V(n) asm volatile("s_waitcnt vmcnt(" #n ")" ::: "memory")
; #define PG8_WAIT_L(n) asm volatile("s_waitcnt lgkmcnt(" #n ")" ::: "memory")
; #define PG8_BAR __builtin_amdgcn_s_barrier()
; #define PG8_SCHED __builtin_amdgcn_sched_barrier(0)
; template <class Epi, class Sched, bool HALFN = false>
; __device__ __forceinline__ void gemm_phase(LAS unsigned char* lds, const Gemm g, const Sched& S, const Epi& E, int wave_s) {
;     ...
;             PG8_LDA(At, 1, 1); PG8_STAGE(PG8_SB(1, 0), b3, voffB); PG8_STAGE(PG8_SB(1, 1), b3 + bh1, voffB); PG8_STAGE(PG8_SA(1, 0), a3, voffA);
;             PG8_WAIT_V(8); PG8_WAIT_L(0); PG8_BAR; PG8_MMA(1, 0, At, B0); if (!HALFN) PG8_MMA(1, 1, At, B1); PG8_BAR; PG8_SCHED;
;         }
;         if (wr == 0) PG8_BAR;
	s_add_i32 s19, s19, s3
	s_nop 2
	v_lshl_add_u64 v[24:25], v[196:197], 0, s[50:51]
	s_mov_b32 m0, s19
	ds_read_b128 v[36:39], v138 offset:49152
	ds_read_b128 v[44:47], v138 offset:50176
	ds_read_b128 v[140:143], v138 offset:51200
	ds_read_b128 v[144:147], v138 offset:52224
	ds_read_b128 v[232:235], v138 offset:53248
	ds_read_b128 v[236:239], v138 offset:54272
	ds_read_b128 v[240:243], v138 offset:55296
	ds_read_b128 v[244:247], v138 offset:56320
	global_load_lds_dwordx4 v[24:25], off
	s_add_i32 m0, s19, 0x2000
	s_add_u32 s28, s28, 0x8080
	v_lshl_add_u64 v[24:25], v[252:253], 0, s[50:51]
	s_addc_u32 s29, s29, 0
	s_add_i32 s19, s21, s3
	global_load_lds_dwordx4 v[24:25], off
	v_lshl_add_u64 v[24:25], s[28:29], 0, v[18:19]
	s_mov_b32 m0, s19
	s_nop 0
	global_load_lds_dwordx4 v[24:25], off
	v_lshl_add_u64 v[24:25], s[28:29], 0, v[136:137]
	s_add_i32 m0, s19, 0x2000
	s_nop 0
	global_load_lds_dwordx4 v[24:25], off
	v_lshl_add_u64 v[24:25], v[202:203], 0, s[50:51]
	s_mov_b32 m0, s46
	s_nop 0
	global_load_lds_dwordx4 v[24:25], off
	v_lshl_add_u64 v[24:25], v[198:199], 0, s[50:51]
	s_mov_b32 m0, s47
	s_nop 0
	global_load_lds_dwordx4 v[24:25], off
	s_waitcnt vmcnt(8)
	s_waitcnt lgkmcnt(0)
	s_barrier
	s_setprio 1
	v_mfma_f32_16x16x32_bf16 v[24:27], v[14:17], v[36:39], v[148:151]
	v_mfma_f32_16x16x32_bf16 v[80:83], v[20:23], v[44:47], v[24:27]
	v_mfma_f32_16x16x32_bf16 v[24:27], v[28:31], v[36:39], v[152:155]
	v_mfma_f32_16x16x32_bf16 v[72:75], v[212:215], v[44:47], v[24:27]
	v_mfma_f32_16x16x32_bf16 v[24:27], v[14:17], v[140:143], v[156:159]
	v_mfma_f32_16x16x32_bf16 v[48:51], v[20:23], v[144:147], v[24:27]
	v_mfma_f32_16x16x32_bf16 v[24:27], v[28:31], v[140:143], v[160:163]
	v_mfma_f32_16x16x32_bf16 v[40:43], v[212:215], v[144:147], v[24:27]
	v_mfma_f32_16x16x32_bf16 v[24:27], v[14:17], v[232:235], v[164:167]
	v_mfma_f32_16x16x32_bf16 v[2:5], v[14:17], v[240:243], v[2:5]
	v_mfma_f32_16x16x32_bf16 v[32:35], v[20:23], v[236:239], v[24:27]
	v_mfma_f32_16x16x32_bf16 v[24:27], v[28:31], v[232:235], v[168:171]
	v_mfma_f32_16x16x32_bf16 v[14:17], v[20:23], v[244:247], v[2:5]
	v_mfma_f32_16x16x32_bf16 v[2:5], v[28:31], v[240:243], v[6:9]
	v_mfma_f32_16x16x32_bf16 v[24:27], v[212:215], v[236:239], v[24:27]
	v_mfma_f32_16x16x32_bf16 v[6:9], v[212:215], v[244:247], v[2:5]
	s_setprio 0
	s_setprio 1
	v_mfma_f32_16x16x32_bf16 v[2:5], v[216:219], v[36:39], v[10:13]
	v_mfma_f32_16x16x32_bf16 v[76:79], v[220:223], v[44:47], v[2:5]
	v_mfma_f32_16x16x32_bf16 v[2:5], v[224:227], v[36:39], v[172:175]
	v_mfma_f32_16x16x32_bf16 v[68:71], v[228:231], v[44:47], v[2:5]
	v_mfma_f32_16x16x32_bf16 v[2:5], v[216:219], v[140:143], v[176:179]
	v_mfma_f32_16x16x32_bf16 v[44:47], v[220:223], v[144:147], v[2:5]
	v_mfma_f32_16x16x32_bf16 v[2:5], v[224:227], v[140:143], v[180:183]
	v_mfma_f32_16x16x32_bf16 v[36:39], v[228:231], v[144:147], v[2:5]
	v_mfma_f32_16x16x32_bf16 v[2:5], v[216:219], v[232:235], v[184:187]
	v_mfma_f32_16x16x32_bf16 v[28:31], v[220:223], v[236:239], v[2:5]
	v_mfma_f32_16x16x32_bf16 v[2:5], v[224:227], v[232:235], v[188:191]
	v_mfma_f32_16x16x32_bf16 v[20:23], v[228:231], v[236:239], v[2:5]
	v_mfma_f32_16x16x32_bf16 v[2:5], v[216:219], v[240:243], v[192:195]
	v_mfma_f32_16x16x32_bf16 v[10:13], v[220:223], v[244:247], v[2:5]
	v_mfma_f32_16x16x32_bf16 v[2:5], v[224:227], v[240:243], v[208:211]
	v_mfma_f32_16x16x32_bf16 v[2:5], v[228:231], v[244:247], v[2:5]
	s_setprio 0
	s_barrier
	s_andn2_b64 vcc, exec, s[14:15]
	s_cbranch_vccnz .LBB0_578
	s_barrier

; #define PG8_STAGE(bufoff, gbase, voff) do { _Pragma("unroll") for (int _i = 0; _i < 2; ++_i) \
;         __builtin_amdgcn_global_load_lds((const unsigned*)((const char*)(gbase) + (voff)[_i]), (LAS unsigned*)(lds + (bufoff) + ldsw + _i * 8192), 16, 0, 0); } while (0)
; #define PG8_LDA(dst, b, h) do { _Pragma("unroll") for (int m = 0; m < 4; ++m) _Pragma("unroll") for (int k = 0; k < 2; ++k) dst[m][k] = *(const LAS bf16x8*)(lds + PG8_SA(b, h) + aoff + m * 2048 + k * 1024); } while (0)
; #define PG8_LDB(dst, b, h) do { _Pragma("unroll") for (int n = 0; n < 2; ++n) _Pragma("unroll") for (int k = 0; k < 2; ++k) dst[n][k] = *(const LAS bf16x8*)(lds + PG8_SB(b, h) + boff + n * 2048 + k * 1024); } while (0)
; #define PG8_WAIT_V(n) asm volatile("s_waitcnt vmcnt(" #n ")" ::: "memory")
; template <class Epi, class Sched, bool HALFN = false>
; __device__ __forceinline__ void gemm_phase(LAS unsigned char* lds, const Gemm g, const Sched& S, const Epi& E, int wave_s) {
;     ...
;         const char* nA = has_next ? (const char*)g.A + (size_t)nxt.z * g.zA * 2 + (size_t)nxt.pm * tstep : cA; const char* nB = has_next ? (const char*)g.Bt + (size_t)nxt.z * g.zB * 2 + (size_t)nxt.pn * (HALFN ? hstep : tstep) : cB;
;         for (int t = 0; t < nt; t += 2) {
;             const bool last = (t == nt - 2);
;             const char* a1 = cA + (size_t)(t + 1) * kstep;
;             const char* a2 = last ? nA : cA + (size_t)(t + 2) * kstep; const char* b2 = last ? nB : cB + (size_t)(t + 2) * kstep;
;             const char* a3 = a2 + kstep; const char* b3 = b2 + kstep;
;             PG8_LDB(B0, 0, 0); if (!HALFN) PG8_LDB(B1, 0, 1); PG8_SCHED; PG8_LDA(At, 0, 0); PG8_STAGE(PG8_SA(1, 1), a1 + hstep, voffA);
;             PG8_WAIT_V(8); PG8_WAIT_L(0); PG8_BAR; PG8_MMA(0, 0, At, B0); if (!HALFN) PG8_MMA(0, 1, At, B1); PG8_BAR; PG8_SCHED;
;             PG8_LDA(At, 0, 1); PG8_STAGE(PG8_SB(0, 0), b2, voffB); PG8_STAGE(PG8_SB(0, 1), b2 + bh1, voffB); PG8_STAGE(PG8_SA(0, 0), a2, voffA);
;             PG8_WAIT_V(8); PG8_WAIT_L(0); PG8_BAR; PG8_MMA(1, 0, At, B0); if (!HALFN) PG8_MMA(1, 1, At, B1); PG8_BAR; PG8_SCHED;
;             PG8_LDB(B0, 1, 0); if (!HALFN) PG8_LDB(B1, 1, 1); PG8_SCHED; PG8_LDA(At, 1, 0); PG8_STAGE(PG8_SA(0, 1), a2 + hstep, voffA);
;             PG8_WAIT_V(8); PG8_WAIT_L(0); PG8_BAR; PG8_MMA(0, 0, At, B0); if (!HALFN) PG8_MMA(0, 1, At, B1); PG8_BAR; PG8_SCHED;
.LBB0_890:
	s_lshl_b64 s[26:27], s[48:49], 20
	s_add_u32 s23, s38, s26
	s_addc_u32 s29, s39, s27
	s_ashr_i32 s21, s20, 31
	s_lshl_b64 s[26:27], s[20:21], 17
	s_add_u32 s26, s23, s26
	s_addc_u32 s27, s29, s27
	s_and_b64 s[4:5], s[4:5], exec
	s_cselect_b32 s5, s27, s37
	s_cselect_b32 s4, s26, s36
	s_add_i32 s48, 0, 0x10000
	v_add_u32_e32 v44, s48, v1
	ds_read_b128 v[46:49], v44
	ds_read_b128 v[50:53], v44 offset:1024
	ds_read_b128 v[54:57], v44 offset:2048
	ds_read_b128 v[58:61], v44 offset:3072
	s_add_u32 s74, s34, 0x20080
	s_addc_u32 s75, s35, 0
	s_add_i32 s52, s31, 0xc000
	v_lshl_add_u64 v[86:87], s[74:75], 0, v[100:101]
	s_mov_b32 m0, s52
	s_add_i32 s21, s31, 0xe000
	ds_read_b128 v[36:39], v176
	ds_read_b128 v[40:43], v176 offset:1024
	ds_read_b128 v[62:65], v176 offset:2048
	ds_read_b128 v[66:69], v176 offset:3072
	ds_read_b128 v[70:73], v176 offset:4096
	ds_read_b128 v[74:77], v176 offset:5120
	ds_read_b128 v[78:81], v176 offset:6144
	ds_read_b128 v[82:85], v176 offset:7168
	global_load_lds_dwordx4 v[86:87], off
	v_lshl_add_u64 v[86:87], s[74:75], 0, v[102:103]
	s_mov_b32 m0, s21
	s_nop 0
	global_load_lds_dwordx4 v[86:87], off
	s_waitcnt vmcnt(14)
	s_waitcnt lgkmcnt(0)
	s_barrier
	s_setprio 1
	v_mfma_f32_16x16x32_bf16 v[86:89], v[46:49], v[36:39], 0
	v_mfma_f32_16x16x32_bf16 v[36:39], v[54:57], v[36:39], 0
	v_mfma_f32_16x16x32_bf16 v[90:93], v[58:61], v[40:43], v[36:39]
	v_mfma_f32_16x16x32_bf16 v[36:39], v[46:49], v[62:65], 0
	v_mfma_f32_16x16x32_bf16 v[94:97], v[50:53], v[66:69], v[36:39]
	v_mfma_f32_16x16x32_bf16 v[36:39], v[54:57], v[62:65], 0
	v_mfma_f32_16x16x32_bf16 v[62:65], v[58:61], v[66:69], v[36:39]
	v_mfma_f32_16x16x32_bf16 v[36:39], v[46:49], v[70:73], 0
	v_mfma_f32_16x16x32_bf16 v[66:69], v[50:53], v[74:77], v[36:39]
	v_mfma_f32_16x16x32_bf16 v[36:39], v[54:57], v[70:73], 0
	v_mfma_f32_16x16x32_bf16 v[70:73], v[58:61], v[74:77], v[36:39]
	v_mfma_f32_16x16x32_bf16 v[36:39], v[46:49], v[78:81], 0
	v_mfma_f32_16x16x32_bf16 v[74:77], v[50:53], v[82:85], v[36:39]
	v_mfma_f32_16x16x32_bf16 v[36:39], v[54:57], v[78:81], 0
	v_mfma_f32_16x16x32_bf16 v[86:89], v[50:53], v[40:43], v[86:89]
	v_mfma_f32_16x16x32_bf16 v[78:81], v[58:61], v[82:85], v[36:39]
	s_setprio 0
	s_barrier
	s_nop 3
	v_lshl_add_u64 v[36:37], s[36:37], 0, v[18:19]
	s_mov_b64 s[74:75], 0x100
	s_add_i32 s48, s48, s41
	v_lshl_add_u64 v[40:41], v[36:37], 0, s[74:75]
	s_mov_b32 m0, s48
	v_lshl_add_u64 v[38:39], s[36:37], 0, v[104:105]
	s_add_i32 s23, s48, 0x2000
	ds_read_b128 v[82:85], v176 offset:16384
	ds_read_b128 v[170:173], v176 offset:17408
	ds_read_b128 v[178:181], v176 offset:18432
	ds_read_b128 v[182:185], v176 offset:19456
	ds_read_b128 v[186:189], v176 offset:20480
	ds_read_b128 v[190:193], v176 offset:21504
	ds_read_b128 v[194:197], v176 offset:22528
	ds_read_b128 v[208:211], v176 offset:23552
	global_load_lds_dwordx4 v[40:41], off
	v_lshl_add_u64 v[42:43], v[38:39], 0, s[74:75]
	s_mov_b32 m0, s23
	s_nop 0
	global_load_lds_dwordx4 v[42:43], off
	v_lshl_add_u64 v[40:41], s[34:35], 0, v[100:101]
	v_lshl_add_u64 v[42:43], v[40:41], 0, s[74:75]
	s_mov_b32 m0, s31
	s_nop 0
	global_load_lds_dwordx4 v[42:43], off
	v_lshl_add_u64 v[42:43], s[34:35], 0, v[102:103]
	v_lshl_add_u64 v[98:99], v[42:43], 0, s[74:75]
	s_mov_b32 m0, s56
	s_nop 0
	global_load_lds_dwordx4 v[98:99], off
	s_waitcnt vmcnt(14)
	s_waitcnt lgkmcnt(0)
	s_barrier
	s_setprio 1
	v_mfma_f32_16x16x32_bf16 v[212:215], v[46:49], v[82:85], 0
	v_mfma_f32_16x16x32_bf16 v[82:85], v[54:57], v[82:85], 0
	v_mfma_f32_16x16x32_bf16 v[212:215], v[50:53], v[170:173], v[212:215]
	v_mfma_f32_16x16x32_bf16 v[82:85], v[58:61], v[170:173], v[82:85]
	v_mfma_f32_16x16x32_bf16 v[170:173], v[46:49], v[178:181], 0
	v_mfma_f32_16x16x32_bf16 v[178:181], v[54:57], v[178:181], 0
	v_mfma_f32_16x16x32_bf16 v[170:173], v[50:53], v[182:185], v[170:173]
	v_mfma_f32_16x16x32_bf16 v[178:181], v[58:61], v[182:185], v[178:181]
	v_mfma_f32_16x16x32_bf16 v[182:185], v[46:49], v[186:189], 0
	v_mfma_f32_16x16x32_bf16 v[46:49], v[46:49], v[194:197], 0
	v_mfma_f32_16x16x32_bf16 v[182:185], v[50:53], v[190:193], v[182:185]
	v_mfma_f32_16x16x32_bf16 v[46:49], v[50:53], v[208:211], v[46:49]
	v_mfma_f32_16x16x32_bf16 v[50:53], v[54:57], v[194:197], 0
	v_mfma_f32_16x16x32_bf16 v[186:189], v[54:57], v[186:189], 0
	v_mfma_f32_16x16x32_bf16 v[50:53], v[58:61], v[208:211], v[50:53]
	v_mfma_f32_16x16x32_bf16 v[186:189], v[58:61], v[190:193], v[186:189]
	s_setprio 0
	s_barrier
	s_add_i32 s29, 0, 0x18000
	v_add_u32_e32 v45, s29, v1
	ds_read_b128 v[54:57], v45
	ds_read_b128 v[58:61], v45 offset:1024
	ds_read_b128 v[190:193], v45 offset:2048
	ds_read_b128 v[194:197], v45 offset:3072
	s_add_u32 s36, s34, 0x20100
	s_addc_u32 s37, s35, 0
	s_mov_b32 m0, s57
	v_lshl_add_u64 v[98:99], s[36:37], 0, v[100:101]
	ds_read_b128 v[208:211], v176 offset:32768
	ds_read_b128 v[216:219], v176 offset:33792
	ds_read_b128 v[220:223], v176 offset:34816
	ds_read_b128 v[224:227], v176 offset:35840
	ds_read_b128 v[228:231], v176 offset:36864
	ds_read_b128 v[232:235], v176 offset:37888
	ds_read_b128 v[236:239], v176 offset:38912
	ds_read_b128 v[240:243], v176 offset:39936
	global_load_lds_dwordx4 v[98:99], off
	v_lshl_add_u64 v[98:99], s[36:37], 0, v[102:103]
	s_mov_b32 m0, s58
	s_nop 0
	global_load_lds_dwordx4 v[98:99], off
	s_waitcnt vmcnt(6)
	s_waitcnt lgkmcnt(0)
	s_barrier
; #define PG8_STAGE(bufoff, gbase, voff) do { _Pragma("unroll") for (int _i = 0; _i < 2; ++_i) \
;         __builtin_amdgcn_global_load_lds((const unsigned*)((const char*)(gbase) + (voff)[_i]), (LAS unsigned*)(lds + (bufoff) + ldsw + _i * 8192), 16, 0, 0); } while (0)
; #define PG8_LDA(dst, b, h) do { _Pragma("unroll") for (int m = 0; m < 4; ++m) _Pragma("unroll") for (int k = 0; k < 2; ++k) dst[m][k] = *(const LAS bf16x8*)(lds + PG8_SA(b, h) + aoff + m * 2048 + k * 1024); } while (0)
; #define PG8_LDB(dst, b, h) do { _Pragma("unroll") for (int n = 0; n < 2; ++n) _Pragma("unroll") for (int k = 0; k < 2; ++k) dst[n][k] = *(const LAS bf16x8*)(lds + PG8_SB(b, h) + boff + n * 2048 + k * 1024); } while (0)
; #define PG8_MMA(ai, bj, At, Bt) do { __builtin_amdgcn_s_setprio(1); _Pragma("unroll") for (int m = 0; m < 4; ++m) _Pragma("unroll") for (int n = 0; n < 2; ++n) _Pragma("unroll") for (int k = 0; k < 2; ++k) \
;         acc[ai][bj][m][n] = __builtin_amdgcn_mfma_f32_16x16x32_bf16(Bt[n][k], At[m][k], acc[ai][bj][m][n], 0, 0, 0); __builtin_amdgcn_s_setprio(0); } while (0)
; template <class Epi, class Sched, bool HALFN = false>
; __device__ __forceinline__ void gemm_phase(LAS unsigned char* lds, const Gemm g, const Sched& S, const Epi& E, int wave_s) {
;     ...
;             PG8_LDB(B0, 0, 0); if (!HALFN) PG8_LDB(B1, 0, 1); PG8_SCHED; PG8_LDA(At, 0, 0); PG8_STAGE(PG8_SA(1, 1), a1 + hstep, voffA);
;             PG8_WAIT_V(8); PG8_WAIT_L(0); PG8_BAR; PG8_MMA(0, 0, At, B0); if (!HALFN) PG8_MMA(0, 1, At, B1); PG8_BAR; PG8_SCHED;
;             PG8_LDA(At, 0, 1); PG8_STAGE(PG8_SB(0, 0), b2, voffB); PG8_STAGE(PG8_SB(0, 1), b2 + bh1, voffB); PG8_STAGE(PG8_SA(0, 0), a2, voffA);
;             PG8_WAIT_V(8); PG8_WAIT_L(0); PG8_BAR; PG8_MMA(1, 0, At, B0); if (!HALFN) PG8_MMA(1, 1, At, B1); PG8_BAR; PG8_SCHED;
;             PG8_LDB(B0, 1, 0); if (!HALFN) PG8_LDB(B1, 1, 1); PG8_SCHED; PG8_LDA(At, 1, 0); PG8_STAGE(PG8_SA(0, 1), a2 + hstep, voffA);
;             PG8_WAIT_V(8); PG8_WAIT_L(0); PG8_BAR; PG8_MMA(0, 0, At, B0); if (!HALFN) PG8_MMA(0, 1, At, B1); PG8_BAR; PG8_SCHED;
;             PG8_LDA(At, 1, 1); PG8_STAGE(PG8_SB(1, 0), b3, voffB); PG8_STAGE(PG8_SB(1, 1), b3 + bh1, voffB); PG8_STAGE(PG8_SA(1, 0), a3, voffA);
;             PG8_WAIT_V(8); PG8_WAIT_L(0); PG8_BAR; PG8_MMA(1, 0, At, B0); if (!HALFN) PG8_MMA(1, 1, At, B1); PG8_BAR; PG8_SCHED;
	s_setprio 1
	v_mfma_f32_16x16x32_bf16 v[86:89], v[54:57], v[208:211], v[86:89]
	v_mfma_f32_16x16x32_bf16 v[90:93], v[190:193], v[208:211], v[90:93]
	v_mfma_f32_16x16x32_bf16 v[94:97], v[54:57], v[220:223], v[94:97]
	v_mfma_f32_16x16x32_bf16 v[62:65], v[190:193], v[220:223], v[62:65]
	v_mfma_f32_16x16x32_bf16 v[66:69], v[54:57], v[228:231], v[66:69]
	v_mfma_f32_16x16x32_bf16 v[70:73], v[190:193], v[228:231], v[70:73]
	v_mfma_f32_16x16x32_bf16 v[74:77], v[54:57], v[236:239], v[74:77]
	v_mfma_f32_16x16x32_bf16 v[78:81], v[190:193], v[236:239], v[78:81]
	v_mfma_f32_16x16x32_bf16 v[86:89], v[58:61], v[216:219], v[86:89]
	v_mfma_f32_16x16x32_bf16 v[90:93], v[194:197], v[216:219], v[90:93]
	v_mfma_f32_16x16x32_bf16 v[94:97], v[58:61], v[224:227], v[94:97]
	v_mfma_f32_16x16x32_bf16 v[62:65], v[194:197], v[224:227], v[62:65]
	v_mfma_f32_16x16x32_bf16 v[66:69], v[58:61], v[232:235], v[66:69]
	v_mfma_f32_16x16x32_bf16 v[70:73], v[194:197], v[232:235], v[70:73]
	v_mfma_f32_16x16x32_bf16 v[74:77], v[58:61], v[240:243], v[74:77]
	v_mfma_f32_16x16x32_bf16 v[78:81], v[194:197], v[240:243], v[78:81]
	s_setprio 0
	s_barrier
	s_mov_b64 s[74:75], 0x180
	s_add_i32 s36, s29, s41
	v_lshl_add_u64 v[98:99], v[36:37], 0, s[74:75]
	s_mov_b32 m0, s36
	s_add_i32 s29, s36, 0x2000
	ds_read_b128 v[208:211], v176 offset:49152
	ds_read_b128 v[216:219], v176 offset:50176
	ds_read_b128 v[220:223], v176 offset:51200
	ds_read_b128 v[224:227], v176 offset:52224
	ds_read_b128 v[228:231], v176 offset:53248
	ds_read_b128 v[232:235], v176 offset:54272
	ds_read_b128 v[236:239], v176 offset:55296
	ds_read_b128 v[240:243], v176 offset:56320
	global_load_lds_dwordx4 v[98:99], off
	v_lshl_add_u64 v[174:175], v[38:39], 0, s[74:75]
	s_mov_b32 m0, s29
	s_nop 0
	global_load_lds_dwordx4 v[174:175], off
	v_lshl_add_u64 v[98:99], v[40:41], 0, s[74:75]
	s_mov_b32 m0, s59
	s_nop 0
	global_load_lds_dwordx4 v[98:99], off
	v_lshl_add_u64 v[98:99], v[42:43], 0, s[74:75]
	s_mov_b32 m0, s62
	s_nop 0
	global_load_lds_dwordx4 v[98:99], off
	s_waitcnt vmcnt(6)
	s_waitcnt lgkmcnt(0)
	s_barrier
	s_setprio 1
	v_mfma_f32_16x16x32_bf16 v[82:85], v[190:193], v[208:211], v[82:85]
	v_mfma_f32_16x16x32_bf16 v[46:49], v[54:57], v[236:239], v[46:49]
	v_mfma_f32_16x16x32_bf16 v[50:53], v[190:193], v[236:239], v[50:53]
	v_mfma_f32_16x16x32_bf16 v[212:215], v[54:57], v[208:211], v[212:215]
	v_mfma_f32_16x16x32_bf16 v[82:85], v[194:197], v[216:219], v[82:85]
	v_mfma_f32_16x16x32_bf16 v[170:173], v[54:57], v[220:223], v[170:173]
	v_mfma_f32_16x16x32_bf16 v[178:181], v[190:193], v[220:223], v[178:181]
	v_mfma_f32_16x16x32_bf16 v[182:185], v[54:57], v[228:231], v[182:185]
	v_mfma_f32_16x16x32_bf16 v[186:189], v[190:193], v[228:231], v[186:189]
	v_mfma_f32_16x16x32_bf16 v[46:49], v[58:61], v[240:243], v[46:49]
	v_mfma_f32_16x16x32_bf16 v[50:53], v[194:197], v[240:243], v[50:53]
	v_mfma_f32_16x16x32_bf16 v[212:215], v[58:61], v[216:219], v[212:215]
	v_mfma_f32_16x16x32_bf16 v[170:173], v[58:61], v[224:227], v[170:173]
	v_mfma_f32_16x16x32_bf16 v[178:181], v[194:197], v[224:227], v[178:181]
	v_mfma_f32_16x16x32_bf16 v[182:185], v[58:61], v[232:235], v[182:185]
	v_mfma_f32_16x16x32_bf16 v[186:189], v[194:197], v[232:235], v[186:189]
	s_setprio 0
	s_barrier
	ds_read_b128 v[54:57], v44
	ds_read_b128 v[58:61], v44 offset:1024
	ds_read_b128 v[190:193], v44 offset:2048
	ds_read_b128 v[194:197], v44 offset:3072
	s_add_u32 s74, s34, 0x20180
	s_addc_u32 s75, s35, 0
	s_mov_b32 m0, s52
	v_lshl_add_u64 v[98:99], s[74:75], 0, v[100:101]
	ds_read_b128 v[208:211], v176
	ds_read_b128 v[216:219], v176 offset:1024
	ds_read_b128 v[220:223], v176 offset:2048
	ds_read_b128 v[224:227], v176 offset:3072
	ds_read_b128 v[228:231], v176 offset:4096
	ds_read_b128 v[232:235], v176 offset:5120
	ds_read_b128 v[236:239], v176 offset:6144
	ds_read_b128 v[240:243], v176 offset:7168
	global_load_lds_dwordx4 v[98:99], off
	v_lshl_add_u64 v[98:99], s[74:75], 0, v[102:103]
	s_mov_b32 m0, s21
	s_nop 0
	global_load_lds_dwordx4 v[98:99], off
	s_waitcnt vmcnt(6)
	s_waitcnt lgkmcnt(0)
	s_barrier
	s_setprio 1
	v_mfma_f32_16x16x32_bf16 v[86:89], v[54:57], v[208:211], v[86:89]
	v_mfma_f32_16x16x32_bf16 v[90:93], v[190:193], v[208:211], v[90:93]
	v_mfma_f32_16x16x32_bf16 v[94:97], v[54:57], v[220:223], v[94:97]
	v_mfma_f32_16x16x32_bf16 v[62:65], v[190:193], v[220:223], v[62:65]
	v_mfma_f32_16x16x32_bf16 v[66:69], v[54:57], v[228:231], v[66:69]
	v_mfma_f32_16x16x32_bf16 v[70:73], v[190:193], v[228:231], v[70:73]
	v_mfma_f32_16x16x32_bf16 v[74:77], v[54:57], v[236:239], v[74:77]
	v_mfma_f32_16x16x32_bf16 v[78:81], v[190:193], v[236:239], v[78:81]
	v_mfma_f32_16x16x32_bf16 v[86:89], v[58:61], v[216:219], v[86:89]
	v_mfma_f32_16x16x32_bf16 v[90:93], v[194:197], v[216:219], v[90:93]
	v_mfma_f32_16x16x32_bf16 v[94:97], v[58:61], v[224:227], v[94:97]
	v_mfma_f32_16x16x32_bf16 v[62:65], v[194:197], v[224:227], v[62:65]
	v_mfma_f32_16x16x32_bf16 v[66:69], v[58:61], v[232:235], v[66:69]
	v_mfma_f32_16x16x32_bf16 v[70:73], v[194:197], v[232:235], v[70:73]
	v_mfma_f32_16x16x32_bf16 v[74:77], v[58:61], v[240:243], v[74:77]
	v_mfma_f32_16x16x32_bf16 v[78:81], v[194:197], v[240:243], v[78:81]
	s_setprio 0
	s_barrier
	s_mov_b64 s[74:75], 0x200
	s_mov_b32 m0, s48
	v_lshl_add_u64 v[98:99], v[36:37], 0, s[74:75]
	ds_read_b128 v[208:211], v176 offset:16384
	ds_read_b128 v[216:219], v176 offset:17408
	ds_read_b128 v[220:223], v176 offset:18432
	ds_read_b128 v[224:227], v176 offset:19456
	ds_read_b128 v[228:231], v176 offset:20480
	ds_read_b128 v[232:235], v176 offset:21504
	ds_read_b128 v[236:239], v176 offset:22528
	ds_read_b128 v[240:243], v176 offset:23552
	global_load_lds_dwordx4 v[98:99], off
	v_lshl_add_u64 v[174:175], v[38:39], 0, s[74:75]
	s_mov_b32 m0, s23
	s_nop 0
	global_load_lds_dwordx4 v[174:175], off
	v_lshl_add_u64 v[98:99], v[40:41], 0, s[74:75]
	s_mov_b32 m0, s31
	s_nop 0
	global_load_lds_dwordx4 v[98:99], off
	v_lshl_add_u64 v[98:99], v[42:43], 0, s[74:75]
	s_mov_b32 m0, s56
	s_nop 0
	global_load_lds_dwordx4 v[98:99], off
	s_waitcnt vmcnt(6)
	s_waitcnt lgkmcnt(0)
	s_barrier
; #define PG8_STAGE(bufoff, gbase, voff) do { _Pragma("unroll") for (int _i = 0; _i < 2; ++_i) \
;         __builtin_amdgcn_global_load_lds((const unsigned*)((const char*)(gbase) + (voff)[_i]), (LAS unsigned*)(lds + (bufoff) + ldsw + _i * 8192), 16, 0, 0); } while (0)
; #define PG8_LDA(dst, b, h) do { _Pragma("unroll") for (int m = 0; m < 4; ++m) _Pragma("unroll") for (int k = 0; k < 2; ++k) dst[m][k] = *(const LAS bf16x8*)(lds + PG8_SA(b, h) + aoff + m * 2048 + k * 1024); } while (0)
; #define PG8_LDB(dst, b, h) do { _Pragma("unroll") for (int n = 0; n < 2; ++n) _Pragma("unroll") for (int k = 0; k < 2; ++k) dst[n][k] = *(const LAS bf16x8*)(lds + PG8_SB(b, h) + boff + n * 2048 + k * 1024); } while (0)
; #define PG8_MMA(ai, bj, At, Bt) do { __builtin_amdgcn_s_setprio(1); _Pragma("unroll") for (int m = 0; m < 4; ++m) _Pragma("unroll") for (int n = 0; n < 2; ++n) _Pragma("unroll") for (int k = 0; k < 2; ++k) \
;         acc[ai][bj][m][n] = __builtin_amdgcn_mfma_f32_16x16x32_bf16(Bt[n][k], At[m][k], acc[ai][bj][m][n], 0, 0, 0); __builtin_amdgcn_s_setprio(0); } while (0)
; template <class Epi, class Sched, bool HALFN = false>
; __device__ __forceinline__ void gemm_phase(LAS unsigned char* lds, const Gemm g, const Sched& S, const Epi& E, int wave_s) {
;     ...
;             PG8_LDB(B0, 0, 0); if (!HALFN) PG8_LDB(B1, 0, 1); PG8_SCHED; PG8_LDA(At, 0, 0); PG8_STAGE(PG8_SA(1, 1), a1 + hstep, voffA);
;             PG8_WAIT_V(8); PG8_WAIT_L(0); PG8_BAR; PG8_MMA(0, 0, At, B0); if (!HALFN) PG8_MMA(0, 1, At, B1); PG8_BAR; PG8_SCHED;
;             PG8_LDA(At, 0, 1); PG8_STAGE(PG8_SB(0, 0), b2, voffB); PG8_STAGE(PG8_SB(0, 1), b2 + bh1, voffB); PG8_STAGE(PG8_SA(0, 0), a2, voffA);
;             PG8_WAIT_V(8); PG8_WAIT_L(0); PG8_BAR; PG8_MMA(1, 0, At, B0); if (!HALFN) PG8_MMA(1, 1, At, B1); PG8_BAR; PG8_SCHED;
;             PG8_LDB(B0, 1, 0); if (!HALFN) PG8_LDB(B1, 1, 1); PG8_SCHED; PG8_LDA(At, 1, 0); PG8_STAGE(PG8_SA(0, 1), a2 + hstep, voffA);
;             PG8_WAIT_V(8); PG8_WAIT_L(0); PG8_BAR; PG8_MMA(0, 0, At, B0); if (!HALFN) PG8_MMA(0, 1, At, B1); PG8_BAR; PG8_SCHED;
;             PG8_LDA(At, 1, 1); PG8_STAGE(PG8_SB(1, 0), b3, voffB); PG8_STAGE(PG8_SB(1, 1), b3 + bh1, voffB); PG8_STAGE(PG8_SA(1, 0), a3, voffA);
;             PG8_WAIT_V(8); PG8_WAIT_L(0); PG8_BAR; PG8_MMA(1, 0, At, B0); if (!HALFN) PG8_MMA(1, 1, At, B1); PG8_BAR; PG8_SCHED;
	s_setprio 1
	v_mfma_f32_16x16x32_bf16 v[82:85], v[190:193], v[208:211], v[82:85]
	v_mfma_f32_16x16x32_bf16 v[46:49], v[54:57], v[236:239], v[46:49]
	v_mfma_f32_16x16x32_bf16 v[50:53], v[190:193], v[236:239], v[50:53]
	v_mfma_f32_16x16x32_bf16 v[212:215], v[54:57], v[208:211], v[212:215]
	v_mfma_f32_16x16x32_bf16 v[82:85], v[194:197], v[216:219], v[82:85]
	v_mfma_f32_16x16x32_bf16 v[170:173], v[54:57], v[220:223], v[170:173]
	v_mfma_f32_16x16x32_bf16 v[178:181], v[190:193], v[220:223], v[178:181]
	v_mfma_f32_16x16x32_bf16 v[182:185], v[54:57], v[228:231], v[182:185]
	v_mfma_f32_16x16x32_bf16 v[186:189], v[190:193], v[228:231], v[186:189]
	v_mfma_f32_16x16x32_bf16 v[46:49], v[58:61], v[240:243], v[46:49]
	v_mfma_f32_16x16x32_bf16 v[50:53], v[194:197], v[240:243], v[50:53]
	v_mfma_f32_16x16x32_bf16 v[212:215], v[58:61], v[216:219], v[212:215]
	v_mfma_f32_16x16x32_bf16 v[170:173], v[58:61], v[224:227], v[170:173]
	v_mfma_f32_16x16x32_bf16 v[178:181], v[194:197], v[224:227], v[178:181]
	v_mfma_f32_16x16x32_bf16 v[182:185], v[58:61], v[232:235], v[182:185]
	v_mfma_f32_16x16x32_bf16 v[186:189], v[194:197], v[232:235], v[186:189]
	s_setprio 0
	s_barrier
	ds_read_b128 v[54:57], v45
	ds_read_b128 v[58:61], v45 offset:1024
	ds_read_b128 v[190:193], v45 offset:2048
	ds_read_b128 v[194:197], v45 offset:3072
	s_add_u32 s74, s34, 0x20200
	s_addc_u32 s75, s35, 0
	s_mov_b32 m0, s57
	v_lshl_add_u64 v[98:99], s[74:75], 0, v[100:101]
	ds_read_b128 v[208:211], v176 offset:32768
	ds_read_b128 v[216:219], v176 offset:33792
	ds_read_b128 v[220:223], v176 offset:34816
	ds_read_b128 v[224:227], v176 offset:35840
	ds_read_b128 v[228:231], v176 offset:36864
	ds_read_b128 v[232:235], v176 offset:37888
	ds_read_b128 v[236:239], v176 offset:38912
	ds_read_b128 v[240:243], v176 offset:39936
	global_load_lds_dwordx4 v[98:99], off
	v_lshl_add_u64 v[98:99], s[74:75], 0, v[102:103]
	s_mov_b32 m0, s58
	s_nop 0
	global_load_lds_dwordx4 v[98:99], off
	s_waitcnt vmcnt(6)
	s_waitcnt lgkmcnt(0)
	s_barrier
	s_setprio 1
	v_mfma_f32_16x16x32_bf16 v[86:89], v[54:57], v[208:211], v[86:89]
	v_mfma_f32_16x16x32_bf16 v[90:93], v[190:193], v[208:211], v[90:93]
	v_mfma_f32_16x16x32_bf16 v[94:97], v[54:57], v[220:223], v[94:97]
	v_mfma_f32_16x16x32_bf16 v[62:65], v[190:193], v[220:223], v[62:65]
	v_mfma_f32_16x16x32_bf16 v[66:69], v[54:57], v[228:231], v[66:69]
	v_mfma_f32_16x16x32_bf16 v[70:73], v[190:193], v[228:231], v[70:73]
	v_mfma_f32_16x16x32_bf16 v[74:77], v[54:57], v[236:239], v[74:77]
	v_mfma_f32_16x16x32_bf16 v[78:81], v[190:193], v[236:239], v[78:81]
	v_mfma_f32_16x16x32_bf16 v[86:89], v[58:61], v[216:219], v[86:89]
	v_mfma_f32_16x16x32_bf16 v[90:93], v[194:197], v[216:219], v[90:93]
	v_mfma_f32_16x16x32_bf16 v[94:97], v[58:61], v[224:227], v[94:97]
	v_mfma_f32_16x16x32_bf16 v[62:65], v[194:197], v[224:227], v[62:65]
	v_mfma_f32_16x16x32_bf16 v[66:69], v[58:61], v[232:235], v[66:69]
	v_mfma_f32_16x16x32_bf16 v[70:73], v[194:197], v[232:235], v[70:73]
	v_mfma_f32_16x16x32_bf16 v[74:77], v[58:61], v[240:243], v[74:77]
	v_mfma_f32_16x16x32_bf16 v[78:81], v[194:197], v[240:243], v[78:81]
	s_setprio 0
	s_barrier
	s_mov_b64 s[74:75], 0x280
	s_mov_b32 m0, s36
	v_lshl_add_u64 v[98:99], v[36:37], 0, s[74:75]
	ds_read_b128 v[208:211], v176 offset:49152
	ds_read_b128 v[216:219], v176 offset:50176
	ds_read_b128 v[220:223], v176 offset:51200
	ds_read_b128 v[224:227], v176 offset:52224
	ds_read_b128 v[228:231], v176 offset:53248
	ds_read_b128 v[232:235], v176 offset:54272
	ds_read_b128 v[236:239], v176 offset:55296
	ds_read_b128 v[240:243], v176 offset:56320
	global_load_lds_dwordx4 v[98:99], off
	v_lshl_add_u64 v[174:175], v[38:39], 0, s[74:75]
	s_mov_b32 m0, s29
	s_nop 0
	global_load_lds_dwordx4 v[174:175], off
	v_lshl_add_u64 v[98:99], v[40:41], 0, s[74:75]
	s_mov_b32 m0, s59
	s_nop 0
	global_load_lds_dwordx4 v[98:99], off
	v_lshl_add_u64 v[98:99], v[42:43], 0, s[74:75]
	s_mov_b32 m0, s62
	s_nop 0
	global_load_lds_dwordx4 v[98:99], off
	s_waitcnt vmcnt(6)
	s_waitcnt lgkmcnt(0)
	s_barrier
	s_setprio 1
	v_mfma_f32_16x16x32_bf16 v[82:85], v[190:193], v[208:211], v[82:85]
	v_mfma_f32_16x16x32_bf16 v[46:49], v[54:57], v[236:239], v[46:49]
	v_mfma_f32_16x16x32_bf16 v[50:53], v[190:193], v[236:239], v[50:53]
	v_mfma_f32_16x16x32_bf16 v[212:215], v[54:57], v[208:211], v[212:215]
	v_mfma_f32_16x16x32_bf16 v[82:85], v[194:197], v[216:219], v[82:85]
	v_mfma_f32_16x16x32_bf16 v[170:173], v[54:57], v[220:223], v[170:173]
	v_mfma_f32_16x16x32_bf16 v[178:181], v[190:193], v[220:223], v[178:181]
	v_mfma_f32_16x16x32_bf16 v[182:185], v[54:57], v[228:231], v[182:185]
	v_mfma_f32_16x16x32_bf16 v[186:189], v[190:193], v[228:231], v[186:189]
	v_mfma_f32_16x16x32_bf16 v[46:49], v[58:61], v[240:243], v[46:49]
	v_mfma_f32_16x16x32_bf16 v[50:53], v[194:197], v[240:243], v[50:53]
	v_mfma_f32_16x16x32_bf16 v[212:215], v[58:61], v[216:219], v[212:215]
	v_mfma_f32_16x16x32_bf16 v[170:173], v[58:61], v[224:227], v[170:173]
	v_mfma_f32_16x16x32_bf16 v[178:181], v[194:197], v[224:227], v[178:181]
	v_mfma_f32_16x16x32_bf16 v[182:185], v[58:61], v[232:235], v[182:185]
	v_mfma_f32_16x16x32_bf16 v[186:189], v[194:197], v[232:235], v[186:189]
	s_setprio 0
	s_barrier
	ds_read_b128 v[54:57], v44
	ds_read_b128 v[58:61], v44 offset:1024
	ds_read_b128 v[190:193], v44 offset:2048
	ds_read_b128 v[194:197], v44 offset:3072
	s_add_u32 s74, s34, 0x20280
	s_addc_u32 s75, s35, 0
	s_mov_b32 m0, s52
	v_lshl_add_u64 v[98:99], s[74:75], 0, v[100:101]
	ds_read_b128 v[208:211], v176
	ds_read_b128 v[216:219], v176 offset:1024
	ds_read_b128 v[220:223], v176 offset:2048
	ds_read_b128 v[224:227], v176 offset:3072
	ds_read_b128 v[228:231], v176 offset:4096
	ds_read_b128 v[232:235], v176 offset:5120
	ds_read_b128 v[236:239], v176 offset:6144
	ds_read_b128 v[240:243], v176 offset:7168
	global_load_lds_dwordx4 v[98:99], off
	v_lshl_add_u64 v[98:99], s[74:75], 0, v[102:103]
	s_mov_b32 m0, s21
	s_nop 0
	global_load_lds_dwordx4 v[98:99], off
	s_waitcnt vmcnt(6)
	s_waitcnt lgkmcnt(0)
	s_barrier
; #define PG8_STAGE(bufoff, gbase, voff) do { _Pragma("unroll") for (int _i = 0; _i < 2; ++_i) \
;         __builtin_amdgcn_global_load_lds((const unsigned*)((const char*)(gbase) + (voff)[_i]), (LAS unsigned*)(lds + (bufoff) + ldsw + _i * 8192), 16, 0, 0); } while (0)
; #define PG8_LDA(dst, b, h) do { _Pragma("unroll") for (int m = 0; m < 4; ++m) _Pragma("unroll") for (int k = 0; k < 2; ++k) dst[m][k] = *(const LAS bf16x8*)(lds + PG8_SA(b, h) + aoff + m * 2048 + k * 1024); } while (0)
; #define PG8_LDB(dst, b, h) do { _Pragma("unroll") for (int n = 0; n < 2; ++n) _Pragma("unroll") for (int k = 0; k < 2; ++k) dst[n][k] = *(const LAS bf16x8*)(lds + PG8_SB(b, h) + boff + n * 2048 + k * 1024); } while (0)
; #define PG8_MMA(ai, bj, At, Bt) do { __builtin_amdgcn_s_setprio(1); _Pragma("unroll") for (int m = 0; m < 4; ++m) _Pragma("unroll") for (int n = 0; n < 2; ++n) _Pragma("unroll") for (int k = 0; k < 2; ++k) \
;         acc[ai][bj][m][n] = __builtin_amdgcn_mfma_f32_16x16x32_bf16(Bt[n][k], At[m][k], acc[ai][bj][m][n], 0, 0, 0); __builtin_amdgcn_s_setprio(0); } while (0)
; template <class Epi, class Sched, bool HALFN = false>
; __device__ __forceinline__ void gemm_phase(LAS unsigned char* lds, const Gemm g, const Sched& S, const Epi& E, int wave_s) {
;     ...
;             PG8_LDB(B0, 0, 0); if (!HALFN) PG8_LDB(B1, 0, 1); PG8_SCHED; PG8_LDA(At, 0, 0); PG8_STAGE(PG8_SA(1, 1), a1 + hstep, voffA);
;             PG8_WAIT_V(8); PG8_WAIT_L(0); PG8_BAR; PG8_MMA(0, 0, At, B0); if (!HALFN) PG8_MMA(0, 1, At, B1); PG8_BAR; PG8_SCHED;
;             PG8_LDA(At, 0, 1); PG8_STAGE(PG8_SB(0, 0), b2, voffB); PG8_STAGE(PG8_SB(0, 1), b2 + bh1, voffB); PG8_STAGE(PG8_SA(0, 0), a2, voffA);
;             PG8_WAIT_V(8); PG8_WAIT_L(0); PG8_BAR; PG8_MMA(1, 0, At, B0); if (!HALFN) PG8_MMA(1, 1, At, B1); PG8_BAR; PG8_SCHED;
;             PG8_LDB(B0, 1, 0); if (!HALFN) PG8_LDB(B1, 1, 1); PG8_SCHED; PG8_LDA(At, 1, 0); PG8_STAGE(PG8_SA(0, 1), a2 + hstep, voffA);
;             PG8_WAIT_V(8); PG8_WAIT_L(0); PG8_BAR; PG8_MMA(0, 0, At, B0); if (!HALFN) PG8_MMA(0, 1, At, B1); PG8_BAR; PG8_SCHED;
;             PG8_LDA(At, 1, 1); PG8_STAGE(PG8_SB(1, 0), b3, voffB); PG8_STAGE(PG8_SB(1, 1), b3 + bh1, voffB); PG8_STAGE(PG8_SA(1, 0), a3, voffA);
;             PG8_WAIT_V(8); PG8_WAIT_L(0); PG8_BAR; PG8_MMA(1, 0, At, B0); if (!HALFN) PG8_MMA(1, 1, At, B1); PG8_BAR; PG8_SCHED;
	s_setprio 1
	v_mfma_f32_16x16x32_bf16 v[86:89], v[54:57], v[208:211], v[86:89]
	v_mfma_f32_16x16x32_bf16 v[90:93], v[190:193], v[208:211], v[90:93]
	v_mfma_f32_16x16x32_bf16 v[94:97], v[54:57], v[220:223], v[94:97]
	v_mfma_f32_16x16x32_bf16 v[62:65], v[190:193], v[220:223], v[62:65]
	v_mfma_f32_16x16x32_bf16 v[66:69], v[54:57], v[228:231], v[66:69]
	v_mfma_f32_16x16x32_bf16 v[70:73], v[190:193], v[228:231], v[70:73]
	v_mfma_f32_16x16x32_bf16 v[74:77], v[54:57], v[236:239], v[74:77]
	v_mfma_f32_16x16x32_bf16 v[78:81], v[190:193], v[236:239], v[78:81]
	v_mfma_f32_16x16x32_bf16 v[86:89], v[58:61], v[216:219], v[86:89]
	v_mfma_f32_16x16x32_bf16 v[90:93], v[194:197], v[216:219], v[90:93]
	v_mfma_f32_16x16x32_bf16 v[94:97], v[58:61], v[224:227], v[94:97]
	v_mfma_f32_16x16x32_bf16 v[62:65], v[194:197], v[224:227], v[62:65]
	v_mfma_f32_16x16x32_bf16 v[66:69], v[58:61], v[232:235], v[66:69]
	v_mfma_f32_16x16x32_bf16 v[70:73], v[194:197], v[232:235], v[70:73]
	v_mfma_f32_16x16x32_bf16 v[74:77], v[58:61], v[240:243], v[74:77]
	v_mfma_f32_16x16x32_bf16 v[78:81], v[194:197], v[240:243], v[78:81]
	s_setprio 0
	s_barrier
	s_mov_b64 s[74:75], 0x300
	s_mov_b32 m0, s48
	v_lshl_add_u64 v[98:99], v[36:37], 0, s[74:75]
	ds_read_b128 v[208:211], v176 offset:16384
	ds_read_b128 v[216:219], v176 offset:17408
	ds_read_b128 v[220:223], v176 offset:18432
	ds_read_b128 v[224:227], v176 offset:19456
	ds_read_b128 v[228:231], v176 offset:20480
	ds_read_b128 v[232:235], v176 offset:21504
	ds_read_b128 v[236:239], v176 offset:22528
	ds_read_b128 v[240:243], v176 offset:23552
	global_load_lds_dwordx4 v[98:99], off
	v_lshl_add_u64 v[174:175], v[38:39], 0, s[74:75]
	s_mov_b32 m0, s23
	s_nop 0
	global_load_lds_dwordx4 v[174:175], off
	v_lshl_add_u64 v[98:99], v[40:41], 0, s[74:75]
	s_mov_b32 m0, s31
	s_nop 0
	global_load_lds_dwordx4 v[98:99], off
	v_lshl_add_u64 v[98:99], v[42:43], 0, s[74:75]
	s_mov_b32 m0, s56
	s_nop 0
	global_load_lds_dwordx4 v[98:99], off
	s_waitcnt vmcnt(6)
	s_waitcnt lgkmcnt(0)
	s_barrier
	s_setprio 1
	v_mfma_f32_16x16x32_bf16 v[82:85], v[190:193], v[208:211], v[82:85]
	v_mfma_f32_16x16x32_bf16 v[46:49], v[54:57], v[236:239], v[46:49]
	v_mfma_f32_16x16x32_bf16 v[50:53], v[190:193], v[236:239], v[50:53]
	v_mfma_f32_16x16x32_bf16 v[212:215], v[54:57], v[208:211], v[212:215]
	v_mfma_f32_16x16x32_bf16 v[82:85], v[194:197], v[216:219], v[82:85]
	v_mfma_f32_16x16x32_bf16 v[170:173], v[54:57], v[220:223], v[170:173]
	v_mfma_f32_16x16x32_bf16 v[178:181], v[190:193], v[220:223], v[178:181]
	v_mfma_f32_16x16x32_bf16 v[182:185], v[54:57], v[228:231], v[182:185]
	v_mfma_f32_16x16x32_bf16 v[186:189], v[190:193], v[228:231], v[186:189]
	v_mfma_f32_16x16x32_bf16 v[46:49], v[58:61], v[240:243], v[46:49]
	v_mfma_f32_16x16x32_bf16 v[50:53], v[194:197], v[240:243], v[50:53]
	v_mfma_f32_16x16x32_bf16 v[212:215], v[58:61], v[216:219], v[212:215]
	v_mfma_f32_16x16x32_bf16 v[170:173], v[58:61], v[224:227], v[170:173]
	v_mfma_f32_16x16x32_bf16 v[178:181], v[194:197], v[224:227], v[178:181]
	v_mfma_f32_16x16x32_bf16 v[182:185], v[58:61], v[232:235], v[182:185]
	v_mfma_f32_16x16x32_bf16 v[186:189], v[194:197], v[232:235], v[186:189]
	s_setprio 0
	s_barrier
	ds_read_b128 v[54:57], v45
	ds_read_b128 v[58:61], v45 offset:1024
	ds_read_b128 v[190:193], v45 offset:2048
	ds_read_b128 v[194:197], v45 offset:3072
	s_add_u32 s74, s34, 0x20300
	s_addc_u32 s75, s35, 0
	s_mov_b32 m0, s57
	v_lshl_add_u64 v[98:99], s[74:75], 0, v[100:101]
	ds_read_b128 v[208:211], v176 offset:32768
	ds_read_b128 v[216:219], v176 offset:33792
	ds_read_b128 v[220:223], v176 offset:34816
	ds_read_b128 v[224:227], v176 offset:35840
	ds_read_b128 v[228:231], v176 offset:36864
	ds_read_b128 v[232:235], v176 offset:37888
	ds_read_b128 v[236:239], v176 offset:38912
	ds_read_b128 v[240:243], v176 offset:39936
	global_load_lds_dwordx4 v[98:99], off
	v_lshl_add_u64 v[98:99], s[74:75], 0, v[102:103]
	s_mov_b32 m0, s58
	s_nop 0
	global_load_lds_dwordx4 v[98:99], off
	s_waitcnt vmcnt(6)
	s_waitcnt lgkmcnt(0)
	s_barrier
	s_setprio 1
	v_mfma_f32_16x16x32_bf16 v[86:89], v[54:57], v[208:211], v[86:89]
	v_mfma_f32_16x16x32_bf16 v[90:93], v[190:193], v[208:211], v[90:93]
	v_mfma_f32_16x16x32_bf16 v[94:97], v[54:57], v[220:223], v[94:97]
	v_mfma_f32_16x16x32_bf16 v[62:65], v[190:193], v[220:223], v[62:65]
	v_mfma_f32_16x16x32_bf16 v[66:69], v[54:57], v[228:231], v[66:69]
	v_mfma_f32_16x16x32_bf16 v[70:73], v[190:193], v[228:231], v[70:73]
	v_mfma_f32_16x16x32_bf16 v[74:77], v[54:57], v[236:239], v[74:77]
	v_mfma_f32_16x16x32_bf16 v[78:81], v[190:193], v[236:239], v[78:81]
	v_mfma_f32_16x16x32_bf16 v[86:89], v[58:61], v[216:219], v[86:89]
	v_mfma_f32_16x16x32_bf16 v[90:93], v[194:197], v[216:219], v[90:93]
	v_mfma_f32_16x16x32_bf16 v[94:97], v[58:61], v[224:227], v[94:97]
	v_mfma_f32_16x16x32_bf16 v[62:65], v[194:197], v[224:227], v[62:65]
	v_mfma_f32_16x16x32_bf16 v[66:69], v[58:61], v[232:235], v[66:69]
	v_mfma_f32_16x16x32_bf16 v[70:73], v[194:197], v[232:235], v[70:73]
	v_mfma_f32_16x16x32_bf16 v[74:77], v[58:61], v[240:243], v[74:77]
	v_mfma_f32_16x16x32_bf16 v[78:81], v[194:197], v[240:243], v[78:81]
	s_setprio 0
	s_barrier
	s_mov_b64 s[74:75], 0x380
	s_mov_b32 m0, s36
	v_lshl_add_u64 v[36:37], v[36:37], 0, s[74:75]
	ds_read_b128 v[208:211], v176 offset:49152
	ds_read_b128 v[216:219], v176 offset:50176
	ds_read_b128 v[220:223], v176 offset:51200
	ds_read_b128 v[224:227], v176 offset:52224
	ds_read_b128 v[228:231], v176 offset:53248
	ds_read_b128 v[232:235], v176 offset:54272
	ds_read_b128 v[236:239], v176 offset:55296
	ds_read_b128 v[240:243], v176 offset:56320
	global_load_lds_dwordx4 v[36:37], off
	v_lshl_add_u64 v[38:39], v[38:39], 0, s[74:75]
	s_mov_b32 m0, s29
	s_nop 0
	global_load_lds_dwordx4 v[38:39], off
	v_lshl_add_u64 v[36:37], v[40:41], 0, s[74:75]
	s_mov_b32 m0, s59
	s_nop 0
	global_load_lds_dwordx4 v[36:37], off
	v_lshl_add_u64 v[36:37], v[42:43], 0, s[74:75]
	s_mov_b32 m0, s62
	s_nop 0
	global_load_lds_dwordx4 v[36:37], off
	s_waitcnt vmcnt(6)
	s_waitcnt lgkmcnt(0)
	s_barrier
; #define PG8_STAGE(bufoff, gbase, voff) do { _Pragma("unroll") for (int _i = 0; _i < 2; ++_i) \
;         __builtin_amdgcn_global_load_lds((const unsigned*)((const char*)(gbase) + (voff)[_i]), (LAS unsigned*)(lds + (bufoff) + ldsw + _i * 8192), 16, 0, 0); } while (0)
; #define PG8_LDA(dst, b, h) do { _Pragma("unroll") for (int m = 0; m < 4; ++m) _Pragma("unroll") for (int k = 0; k < 2; ++k) dst[m][k] = *(const LAS bf16x8*)(lds + PG8_SA(b, h) + aoff + m * 2048 + k * 1024); } while (0)
; #define PG8_LDB(dst, b, h) do { _Pragma("unroll") for (int n = 0; n < 2; ++n) _Pragma("unroll") for (int k = 0; k < 2; ++k) dst[n][k] = *(const LAS bf16x8*)(lds + PG8_SB(b, h) + boff + n * 2048 + k * 1024); } while (0)
; #define PG8_WAIT_V(n) asm volatile("s_waitcnt vmcnt(" #n ")" ::: "memory")
; #define PG8_WAIT_L(n) asm volatile("s_waitcnt lgkmcnt(" #n ")" ::: "memory")
; #define PG8_BAR __builtin_amdgcn_s_barrier()
; template <class Epi, class Sched, bool HALFN = false>
; __device__ __forceinline__ void gemm_phase(LAS unsigned char* lds, const Gemm g, const Sched& S, const Epi& E, int wave_s) {
;     ...
;             const char* a2 = last ? nA : cA + (size_t)(t + 2) * kstep; const char* b2 = last ? nB : cB + (size_t)(t + 2) * kstep;
;             const char* a3 = a2 + kstep; const char* b3 = b2 + kstep;
;             PG8_LDB(B0, 0, 0); if (!HALFN) PG8_LDB(B1, 0, 1); PG8_SCHED; PG8_LDA(At, 0, 0); PG8_STAGE(PG8_SA(1, 1), a1 + hstep, voffA);
;             PG8_WAIT_V(8); PG8_WAIT_L(0); PG8_BAR; PG8_MMA(0, 0, At, B0); if (!HALFN) PG8_MMA(0, 1, At, B1); PG8_BAR; PG8_SCHED;
;             PG8_LDA(At, 0, 1); PG8_STAGE(PG8_SB(0, 0), b2, voffB); PG8_STAGE(PG8_SB(0, 1), b2 + bh1, voffB); PG8_STAGE(PG8_SA(0, 0), a2, voffA);
;             PG8_WAIT_V(8); PG8_WAIT_L(0); PG8_BAR; PG8_MMA(1, 0, At, B0); if (!HALFN) PG8_MMA(1, 1, At, B1); PG8_BAR; PG8_SCHED;
;             PG8_LDB(B0, 1, 0); if (!HALFN) PG8_LDB(B1, 1, 1); PG8_SCHED; PG8_LDA(At, 1, 0); PG8_STAGE(PG8_SA(0, 1), a2 + hstep, voffA);
;             PG8_WAIT_V(8); PG8_WAIT_L(0); PG8_BAR; PG8_MMA(0, 0, At, B0); if (!HALFN) PG8_MMA(0, 1, At, B1); PG8_BAR; PG8_SCHED;
;             PG8_LDA(At, 1, 1); PG8_STAGE(PG8_SB(1, 0), b3, voffB); PG8_STAGE(PG8_SB(1, 1), b3 + bh1, voffB); PG8_STAGE(PG8_SA(1, 0), a3, voffA);
;             PG8_WAIT_V(8); PG8_WAIT_L(0); PG8_BAR; PG8_MMA(1, 0, At, B0); if (!HALFN) PG8_MMA(1, 1, At, B1); PG8_BAR; PG8_SCHED;
	s_setprio 1
	v_mfma_f32_16x16x32_bf16 v[36:39], v[54:57], v[208:211], v[212:215]
	v_mfma_f32_16x16x32_bf16 v[40:43], v[190:193], v[208:211], v[82:85]
	v_mfma_f32_16x16x32_bf16 v[82:85], v[54:57], v[220:223], v[170:173]
	v_mfma_f32_16x16x32_bf16 v[46:49], v[54:57], v[236:239], v[46:49]
	v_mfma_f32_16x16x32_bf16 v[50:53], v[190:193], v[236:239], v[50:53]
	v_mfma_f32_16x16x32_bf16 v[36:39], v[58:61], v[216:219], v[36:39]
	v_mfma_f32_16x16x32_bf16 v[40:43], v[194:197], v[216:219], v[40:43]
	v_mfma_f32_16x16x32_bf16 v[82:85], v[58:61], v[224:227], v[82:85]
	v_mfma_f32_16x16x32_bf16 v[170:173], v[190:193], v[220:223], v[178:181]
	v_mfma_f32_16x16x32_bf16 v[178:181], v[54:57], v[228:231], v[182:185]
	v_mfma_f32_16x16x32_bf16 v[182:185], v[190:193], v[228:231], v[186:189]
	v_mfma_f32_16x16x32_bf16 v[46:49], v[58:61], v[240:243], v[46:49]
	v_mfma_f32_16x16x32_bf16 v[50:53], v[194:197], v[240:243], v[50:53]
	v_mfma_f32_16x16x32_bf16 v[170:173], v[194:197], v[224:227], v[170:173]
	v_mfma_f32_16x16x32_bf16 v[178:181], v[58:61], v[232:235], v[178:181]
	v_mfma_f32_16x16x32_bf16 v[182:185], v[194:197], v[232:235], v[182:185]
	s_setprio 0
	s_barrier
	ds_read_b128 v[54:57], v44
	ds_read_b128 v[58:61], v44 offset:1024
	ds_read_b128 v[186:189], v44 offset:2048
	ds_read_b128 v[190:193], v44 offset:3072
	s_add_u32 s34, s34, 0x20380
	s_addc_u32 s35, s35, 0
	s_mov_b32 m0, s52
	v_lshl_add_u64 v[98:99], s[34:35], 0, v[100:101]
	ds_read_b128 v[194:197], v176
	ds_read_b128 v[208:211], v176 offset:1024
	ds_read_b128 v[212:215], v176 offset:2048
	ds_read_b128 v[216:219], v176 offset:3072
	ds_read_b128 v[220:223], v176 offset:4096
	ds_read_b128 v[224:227], v176 offset:5120
	ds_read_b128 v[228:231], v176 offset:6144
	ds_read_b128 v[232:235], v176 offset:7168
	global_load_lds_dwordx4 v[98:99], off
	v_lshl_add_u64 v[98:99], s[34:35], 0, v[102:103]
	s_mov_b32 m0, s21
	s_nop 0
	global_load_lds_dwordx4 v[98:99], off
	s_waitcnt vmcnt(6)
	s_waitcnt lgkmcnt(0)
	s_barrier
	s_setprio 1
	v_mfma_f32_16x16x32_bf16 v[86:89], v[54:57], v[194:197], v[86:89]
	v_mfma_f32_16x16x32_bf16 v[90:93], v[186:189], v[194:197], v[90:93]
	v_mfma_f32_16x16x32_bf16 v[62:65], v[186:189], v[212:215], v[62:65]
	v_mfma_f32_16x16x32_bf16 v[66:69], v[54:57], v[220:223], v[66:69]
	v_mfma_f32_16x16x32_bf16 v[70:73], v[186:189], v[220:223], v[70:73]
	v_mfma_f32_16x16x32_bf16 v[74:77], v[54:57], v[228:231], v[74:77]
	v_mfma_f32_16x16x32_bf16 v[86:89], v[58:61], v[208:211], v[86:89]
	v_mfma_f32_16x16x32_bf16 v[90:93], v[190:193], v[208:211], v[90:93]
	v_mfma_f32_16x16x32_bf16 v[94:97], v[54:57], v[212:215], v[94:97]
	v_mfma_f32_16x16x32_bf16 v[62:65], v[190:193], v[216:219], v[62:65]
	v_mfma_f32_16x16x32_bf16 v[66:69], v[58:61], v[224:227], v[66:69]
	v_mfma_f32_16x16x32_bf16 v[70:73], v[190:193], v[224:227], v[70:73]
	v_mfma_f32_16x16x32_bf16 v[208:211], v[58:61], v[232:235], v[74:77]
	v_mfma_f32_16x16x32_bf16 v[74:77], v[186:189], v[228:231], v[78:81]
	v_mfma_f32_16x16x32_bf16 v[194:197], v[58:61], v[216:219], v[94:97]
	v_mfma_f32_16x16x32_bf16 v[212:215], v[190:193], v[232:235], v[74:77]
	s_setprio 0
	s_barrier
	s_mov_b32 m0, s48
	v_lshl_add_u64 v[174:175], s[4:5], 0, v[18:19]
	s_nop 1
	ds_read_b128 v[74:77], v176 offset:16384
	ds_read_b128 v[78:81], v176 offset:17408
	ds_read_b128 v[94:97], v176 offset:18432
	ds_read_b128 v[216:219], v176 offset:19456
	ds_read_b128 v[220:223], v176 offset:20480
	ds_read_b128 v[224:227], v176 offset:21504
	ds_read_b128 v[228:231], v176 offset:22528
	ds_read_b128 v[232:235], v176 offset:23552
	global_load_lds_dwordx4 v[174:175], off
	v_lshl_add_u64 v[198:199], s[4:5], 0, v[104:105]
	s_mov_b32 m0, s23
	v_lshl_add_u64 v[202:203], s[24:25], 0, v[100:101]
	global_load_lds_dwordx4 v[198:199], off
	v_lshl_add_u64 v[248:249], s[24:25], 0, v[102:103]
	s_mov_b32 m0, s31
	s_nop 0
	global_load_lds_dwordx4 v[202:203], off
	s_mov_b32 m0, s56
	s_nop 0
	global_load_lds_dwordx4 v[248:249], off
	s_waitcnt vmcnt(6)
	s_waitcnt lgkmcnt(0)
	s_barrier
	s_setprio 1
	v_mfma_f32_16x16x32_bf16 v[36:39], v[54:57], v[74:77], v[36:39]
	v_mfma_f32_16x16x32_bf16 v[40:43], v[186:189], v[74:77], v[40:43]
	v_mfma_f32_16x16x32_bf16 v[74:77], v[54:57], v[94:97], v[82:85]
	v_mfma_f32_16x16x32_bf16 v[236:239], v[58:61], v[216:219], v[74:77]
	v_mfma_f32_16x16x32_bf16 v[74:77], v[186:189], v[94:97], v[170:173]
	v_mfma_f32_16x16x32_bf16 v[170:173], v[190:193], v[216:219], v[74:77]
	v_mfma_f32_16x16x32_bf16 v[74:77], v[54:57], v[220:223], v[178:181]
	v_mfma_f32_16x16x32_bf16 v[46:49], v[54:57], v[228:231], v[46:49]
	v_mfma_f32_16x16x32_bf16 v[36:39], v[58:61], v[78:81], v[36:39]
	v_mfma_f32_16x16x32_bf16 v[40:43], v[190:193], v[78:81], v[40:43]
	v_mfma_f32_16x16x32_bf16 v[178:181], v[58:61], v[224:227], v[74:77]
	v_mfma_f32_16x16x32_bf16 v[74:77], v[186:189], v[220:223], v[182:185]
	v_mfma_f32_16x16x32_bf16 v[216:219], v[58:61], v[232:235], v[46:49]
	v_mfma_f32_16x16x32_bf16 v[46:49], v[186:189], v[228:231], v[50:53]
	v_mfma_f32_16x16x32_bf16 v[182:185], v[190:193], v[224:227], v[74:77]
	v_mfma_f32_16x16x32_bf16 v[186:189], v[190:193], v[232:235], v[46:49]
	s_setprio 0
	s_barrier
; #define PG8_STAGE(bufoff, gbase, voff) do { _Pragma("unroll") for (int _i = 0; _i < 2; ++_i) \
;         __builtin_amdgcn_global_load_lds((const unsigned*)((const char*)(gbase) + (voff)[_i]), (LAS unsigned*)(lds + (bufoff) + ldsw + _i * 8192), 16, 0, 0); } while (0)
; #define PG8_LDA(dst, b, h) do { _Pragma("unroll") for (int m = 0; m < 4; ++m) _Pragma("unroll") for (int k = 0; k < 2; ++k) dst[m][k] = *(const LAS bf16x8*)(lds + PG8_SA(b, h) + aoff + m * 2048 + k * 1024); } while (0)
; #define PG8_LDB(dst, b, h) do { _Pragma("unroll") for (int n = 0; n < 2; ++n) _Pragma("unroll") for (int k = 0; k < 2; ++k) dst[n][k] = *(const LAS bf16x8*)(lds + PG8_SB(b, h) + boff + n * 2048 + k * 1024); } while (0)
; #define PG8_MMA(ai, bj, At, Bt) do { __builtin_amdgcn_s_setprio(1); _Pragma("unroll") for (int m = 0; m < 4; ++m) _Pragma("unroll") for (int n = 0; n < 2; ++n) _Pragma("unroll") for (int k = 0; k < 2; ++k) \
;         acc[ai][bj][m][n] = __builtin_amdgcn_mfma_f32_16x16x32_bf16(Bt[n][k], At[m][k], acc[ai][bj][m][n], 0, 0, 0); __builtin_amdgcn_s_setprio(0); } while (0)
; #define PG8_WAIT_V(n) asm volatile("s_waitcnt vmcnt(" #n ")" ::: "memory")
; #define PG8_WAIT_L(n) asm volatile("s_waitcnt lgkmcnt(" #n ")" ::: "memory")
; #define PG8_BAR __builtin_amdgcn_s_barrier()
; #define PG8_SCHED __builtin_amdgcn_sched_barrier(0)
; template <class Epi, class Sched, bool HALFN = false>
; __device__ __forceinline__ void gemm_phase(LAS unsigned char* lds, const Gemm g, const Sched& S, const Epi& E, int wave_s) {
;     ...
;             PG8_LDA(At, 0, 1); PG8_STAGE(PG8_SB(0, 0), b2, voffB); PG8_STAGE(PG8_SB(0, 1), b2 + bh1, voffB); PG8_STAGE(PG8_SA(0, 0), a2, voffA);
;             PG8_WAIT_V(8); PG8_WAIT_L(0); PG8_BAR; PG8_MMA(1, 0, At, B0); if (!HALFN) PG8_MMA(1, 1, At, B1); PG8_BAR; PG8_SCHED;
;             PG8_LDB(B0, 1, 0); if (!HALFN) PG8_LDB(B1, 1, 1); PG8_SCHED; PG8_LDA(At, 1, 0); PG8_STAGE(PG8_SA(0, 1), a2 + hstep, voffA);
;             PG8_WAIT_V(8); PG8_WAIT_L(0); PG8_BAR; PG8_MMA(0, 0, At, B0); if (!HALFN) PG8_MMA(0, 1, At, B1); PG8_BAR; PG8_SCHED;
;             PG8_LDA(At, 1, 1); PG8_STAGE(PG8_SB(1, 0), b3, voffB); PG8_STAGE(PG8_SB(1, 1), b3 + bh1, voffB); PG8_STAGE(PG8_SA(1, 0), a3, voffA);
;             PG8_WAIT_V(8); PG8_WAIT_L(0); PG8_BAR; PG8_MMA(1, 0, At, B0); if (!HALFN) PG8_MMA(1, 1, At, B1); PG8_BAR; PG8_SCHED;
;         }
;         if (wr == 0) PG8_BAR;
	ds_read_b128 v[190:193], v45
	ds_read_b128 v[220:223], v45 offset:1024
	ds_read_b128 v[224:227], v45 offset:2048
	ds_read_b128 v[228:231], v45 offset:3072
	s_add_u32 s4, s24, 0x20000
	s_addc_u32 s5, s25, 0
	s_mov_b32 m0, s57
	v_lshl_add_u64 v[60:61], s[4:5], 0, v[100:101]
	ds_read_b128 v[44:47], v176 offset:32768
	ds_read_b128 v[48:51], v176 offset:33792
	ds_read_b128 v[52:55], v176 offset:34816
	ds_read_b128 v[56:59], v176 offset:35840
	ds_read_b128 v[74:77], v176 offset:36864
	ds_read_b128 v[232:235], v176 offset:37888
	ds_read_b128 v[240:243], v176 offset:38912
	ds_read_b128 v[244:247], v176 offset:39936
	global_load_lds_dwordx4 v[60:61], off
	v_lshl_add_u64 v[60:61], s[4:5], 0, v[102:103]
	s_mov_b32 m0, s58
	s_nop 0
	global_load_lds_dwordx4 v[60:61], off
	s_waitcnt vmcnt(6)
	s_waitcnt lgkmcnt(0)
	s_barrier
	s_setprio 1
	v_mfma_f32_16x16x32_bf16 v[78:81], v[190:193], v[44:47], v[86:89]
	v_mfma_f32_16x16x32_bf16 v[44:47], v[224:227], v[44:47], v[90:93]
	v_mfma_f32_16x16x32_bf16 v[92:95], v[228:231], v[48:51], v[44:47]
	v_mfma_f32_16x16x32_bf16 v[44:47], v[190:193], v[52:55], v[194:197]
	v_mfma_f32_16x16x32_bf16 v[88:91], v[220:223], v[56:59], v[44:47]
	v_mfma_f32_16x16x32_bf16 v[44:47], v[224:227], v[52:55], v[62:65]
	v_mfma_f32_16x16x32_bf16 v[84:87], v[228:231], v[56:59], v[44:47]
	v_mfma_f32_16x16x32_bf16 v[44:47], v[190:193], v[74:77], v[66:69]
	v_mfma_f32_16x16x32_bf16 v[96:99], v[220:223], v[48:51], v[78:81]
	v_mfma_f32_16x16x32_bf16 v[80:83], v[220:223], v[232:235], v[44:47]
	v_mfma_f32_16x16x32_bf16 v[44:47], v[224:227], v[74:77], v[70:73]
	v_mfma_f32_16x16x32_bf16 v[76:79], v[228:231], v[232:235], v[44:47]
	v_mfma_f32_16x16x32_bf16 v[44:47], v[190:193], v[240:243], v[208:211]
	v_mfma_f32_16x16x32_bf16 v[72:75], v[220:223], v[244:247], v[44:47]
	v_mfma_f32_16x16x32_bf16 v[44:47], v[224:227], v[240:243], v[212:215]
	v_mfma_f32_16x16x32_bf16 v[68:71], v[228:231], v[244:247], v[44:47]
	s_setprio 0
	s_barrier
	s_mov_b32 m0, s36
	v_lshl_add_u64 v[56:57], v[174:175], 0, s[50:51]
	s_nop 2
	ds_read_b128 v[44:47], v176 offset:49152
	ds_read_b128 v[48:51], v176 offset:50176
	ds_read_b128 v[52:55], v176 offset:51200
	ds_read_b128 v[194:197], v176 offset:52224
	ds_read_b128 v[208:211], v176 offset:53248
	ds_read_b128 v[212:215], v176 offset:54272
	ds_read_b128 v[232:235], v176 offset:55296
	ds_read_b128 v[240:243], v176 offset:56320
	global_load_lds_dwordx4 v[56:57], off
	v_lshl_add_u64 v[58:59], v[198:199], 0, s[50:51]
	s_mov_b32 m0, s29
	s_nop 0
	global_load_lds_dwordx4 v[58:59], off
	v_lshl_add_u64 v[56:57], v[202:203], 0, s[50:51]
	s_mov_b32 m0, s59
	s_nop 0
	global_load_lds_dwordx4 v[56:57], off
	v_lshl_add_u64 v[56:57], v[248:249], 0, s[50:51]
	s_mov_b32 m0, s62
	s_nop 0
	global_load_lds_dwordx4 v[56:57], off
	s_waitcnt vmcnt(6)
	s_waitcnt lgkmcnt(0)
	s_barrier
	s_setprio 1
	v_mfma_f32_16x16x32_bf16 v[36:39], v[190:193], v[44:47], v[36:39]
	v_mfma_f32_16x16x32_bf16 v[64:67], v[220:223], v[48:51], v[36:39]
	v_mfma_f32_16x16x32_bf16 v[36:39], v[224:227], v[44:47], v[40:43]
	v_mfma_f32_16x16x32_bf16 v[60:63], v[228:231], v[48:51], v[36:39]
	v_mfma_f32_16x16x32_bf16 v[36:39], v[190:193], v[52:55], v[236:239]
	v_mfma_f32_16x16x32_bf16 v[56:59], v[220:223], v[194:197], v[36:39]
	v_mfma_f32_16x16x32_bf16 v[36:39], v[224:227], v[52:55], v[170:173]
	v_mfma_f32_16x16x32_bf16 v[52:55], v[228:231], v[194:197], v[36:39]
	v_mfma_f32_16x16x32_bf16 v[36:39], v[190:193], v[208:211], v[178:181]
	v_mfma_f32_16x16x32_bf16 v[48:51], v[220:223], v[212:215], v[36:39]
	v_mfma_f32_16x16x32_bf16 v[36:39], v[224:227], v[208:211], v[182:185]
	v_mfma_f32_16x16x32_bf16 v[44:47], v[228:231], v[212:215], v[36:39]
	v_mfma_f32_16x16x32_bf16 v[36:39], v[190:193], v[232:235], v[216:219]
	v_mfma_f32_16x16x32_bf16 v[40:43], v[220:223], v[240:243], v[36:39]
	v_mfma_f32_16x16x32_bf16 v[36:39], v[224:227], v[232:235], v[186:189]
	v_mfma_f32_16x16x32_bf16 v[36:39], v[228:231], v[240:243], v[36:39]
	s_setprio 0
	s_barrier
	s_andn2_b64 vcc, exec, s[18:19]
	s_cbranch_vccnz .LBB0_892
	s_barrier

; #define PG8_STAGE(bufoff, gbase, voff) do { _Pragma("unroll") for (int _i = 0; _i < 2; ++_i) \
;         __builtin_amdgcn_global_load_lds((const unsigned*)((const char*)(gbase) + (voff)[_i]), (LAS unsigned*)(lds + (bufoff) + ldsw + _i * 8192), 16, 0, 0); } while (0)
; #define PG8_LDA(dst, b, h) do { _Pragma("unroll") for (int m = 0; m < 4; ++m) _Pragma("unroll") for (int k = 0; k < 2; ++k) dst[m][k] = *(const LAS bf16x8*)(lds + PG8_SA(b, h) + aoff + m * 2048 + k * 1024); } while (0)
; #define PG8_LDB(dst, b, h) do { _Pragma("unroll") for (int n = 0; n < 2; ++n) _Pragma("unroll") for (int k = 0; k < 2; ++k) dst[n][k] = *(const LAS bf16x8*)(lds + PG8_SB(b, h) + boff + n * 2048 + k * 1024); } while (0)
; #define PG8_WAIT_V(n) asm volatile("s_waitcnt vmcnt(" #n ")" ::: "memory")
; #define PG8_WAIT_L(n) asm volatile("s_waitcnt lgkmcnt(" #n ")" ::: "memory")
; #define PG8_BAR __builtin_amdgcn_s_barrier()
; #define PG8_SCHED __builtin_amdgcn_sched_barrier(0)
; template <class Epi, class Sched, bool HALFN = false>
; __device__ __forceinline__ void gemm_phase(LAS unsigned char* lds, const Gemm g, const Sched& S, const Epi& E, int wave_s) {
;     ...
;         const bool has_next = S.next(ui + 1, nxt);
;         const char* nA = has_next ? (const char*)g.A + (size_t)nxt.z * g.zA * 2 + (size_t)nxt.pm * tstep : cA; const char* nB = has_next ? (const char*)g.Bt + (size_t)nxt.z * g.zB * 2 + (size_t)nxt.pn * (HALFN ? hstep : tstep) : cB;
;         for (int t = 0; t < nt; t += 2) {
;             const bool last = (t == nt - 2);
;             const char* a1 = cA + (size_t)(t + 1) * kstep;
;             const char* a2 = last ? nA : cA + (size_t)(t + 2) * kstep; const char* b2 = last ? nB : cB + (size_t)(t + 2) * kstep;
;             const char* a3 = a2 + kstep; const char* b3 = b2 + kstep;
;             PG8_LDB(B0, 0, 0); if (!HALFN) PG8_LDB(B1, 0, 1); PG8_SCHED; PG8_LDA(At, 0, 0); PG8_STAGE(PG8_SA(1, 1), a1 + hstep, voffA);
;             PG8_WAIT_V(8); PG8_WAIT_L(0); PG8_BAR; PG8_MMA(0, 0, At, B0); if (!HALFN) PG8_MMA(0, 1, At, B1); PG8_BAR; PG8_SCHED;
;             PG8_LDA(At, 0, 1); PG8_STAGE(PG8_SB(0, 0), b2, voffB); PG8_STAGE(PG8_SB(0, 1), b2 + bh1, voffB); PG8_STAGE(PG8_SA(0, 0), a2, voffA);
;             PG8_WAIT_V(8); PG8_WAIT_L(0); PG8_BAR; PG8_MMA(1, 0, At, B0); if (!HALFN) PG8_MMA(1, 1, At, B1); PG8_BAR; PG8_SCHED;
.LBB0_985:
	s_add_u32 s34, s6, 0xfffc0080
	s_addc_u32 s35, s7, -1
	s_add_i32 s53, 0, 0x10000
	s_cmp_eq_u32 s52, 12
	s_cselect_b32 s37, s5, s35
	s_cselect_b32 s36, s25, s34
	v_add_u32_e32 v18, s53, v1
	s_cselect_b32 s35, s23, s48
	s_cselect_b32 s34, s31, s42
	s_add_i32 s66, 0, 0x14000
	ds_read_b128 v[132:135], v18
	ds_read_b128 v[136:139], v18 offset:1024
	ds_read_b128 v[140:143], v18 offset:2048
	ds_read_b128 v[144:147], v18 offset:3072
	v_add_u32_e32 v18, s66, v1
	ds_read_b128 v[148:151], v18
	ds_read_b128 v[152:155], v18 offset:1024
	ds_read_b128 v[156:159], v18 offset:2048
	ds_read_b128 v[160:163], v18 offset:3072
	v_lshl_add_u64 v[198:199], s[6:7], 0, v[172:173]
	s_add_i32 m0, s45, 0xc000
	ds_read_b128 v[176:179], v184
	ds_read_b128 v[180:183], v184 offset:1024
	ds_read_b128 v[186:189], v184 offset:2048
	ds_read_b128 v[190:193], v184 offset:3072
	ds_read_b128 v[194:197], v184 offset:4096
	ds_read_b128 v[208:211], v184 offset:5120
	ds_read_b128 v[212:215], v184 offset:6144
	ds_read_b128 v[216:219], v184 offset:7168
	global_load_lds_dwordx4 v[198:199], off
	v_lshl_add_u64 v[198:199], s[6:7], 0, v[174:175]
	s_add_i32 m0, s45, 0xe000
	s_nop 0
	global_load_lds_dwordx4 v[198:199], off
	s_waitcnt vmcnt(8)
	s_waitcnt lgkmcnt(0)
	s_barrier
	s_setprio 1
	v_mfma_f32_16x16x32_bf16 v[128:131], v[132:135], v[176:179], v[128:131]
	v_mfma_f32_16x16x32_bf16 v[124:127], v[140:143], v[176:179], v[124:127]
	v_mfma_f32_16x16x32_bf16 v[112:115], v[132:135], v[186:189], v[112:115]
	v_mfma_f32_16x16x32_bf16 v[108:111], v[140:143], v[186:189], v[108:111]
	v_mfma_f32_16x16x32_bf16 v[96:99], v[132:135], v[194:197], v[96:99]
	v_mfma_f32_16x16x32_bf16 v[92:95], v[140:143], v[194:197], v[92:95]
	v_mfma_f32_16x16x32_bf16 v[80:83], v[132:135], v[212:215], v[80:83]
	v_mfma_f32_16x16x32_bf16 v[76:79], v[140:143], v[212:215], v[76:79]
	v_mfma_f32_16x16x32_bf16 v[128:131], v[136:139], v[180:183], v[128:131]
	v_mfma_f32_16x16x32_bf16 v[124:127], v[144:147], v[180:183], v[124:127]
	v_mfma_f32_16x16x32_bf16 v[112:115], v[136:139], v[190:193], v[112:115]
	v_mfma_f32_16x16x32_bf16 v[108:111], v[144:147], v[190:193], v[108:111]
	v_mfma_f32_16x16x32_bf16 v[96:99], v[136:139], v[208:211], v[96:99]
	v_mfma_f32_16x16x32_bf16 v[92:95], v[144:147], v[208:211], v[92:95]
	v_mfma_f32_16x16x32_bf16 v[80:83], v[136:139], v[216:219], v[80:83]
	v_mfma_f32_16x16x32_bf16 v[76:79], v[144:147], v[216:219], v[76:79]
	s_setprio 0
	s_setprio 1
	v_mfma_f32_16x16x32_bf16 v[120:123], v[148:151], v[176:179], v[120:123]
	v_mfma_f32_16x16x32_bf16 v[116:119], v[156:159], v[176:179], v[116:119]
	v_mfma_f32_16x16x32_bf16 v[104:107], v[148:151], v[186:189], v[104:107]
	v_mfma_f32_16x16x32_bf16 v[100:103], v[156:159], v[186:189], v[100:103]
	v_mfma_f32_16x16x32_bf16 v[88:91], v[148:151], v[194:197], v[88:91]
	v_mfma_f32_16x16x32_bf16 v[84:87], v[156:159], v[194:197], v[84:87]
	v_mfma_f32_16x16x32_bf16 v[72:75], v[148:151], v[212:215], v[72:75]
	v_mfma_f32_16x16x32_bf16 v[68:71], v[156:159], v[212:215], v[68:71]
	v_mfma_f32_16x16x32_bf16 v[120:123], v[152:155], v[180:183], v[120:123]
	v_mfma_f32_16x16x32_bf16 v[116:119], v[160:163], v[180:183], v[116:119]
	v_mfma_f32_16x16x32_bf16 v[104:107], v[152:155], v[190:193], v[104:107]
	v_mfma_f32_16x16x32_bf16 v[100:103], v[160:163], v[190:193], v[100:103]
	v_mfma_f32_16x16x32_bf16 v[88:91], v[152:155], v[208:211], v[88:91]
	v_mfma_f32_16x16x32_bf16 v[84:87], v[160:163], v[208:211], v[84:87]
	v_mfma_f32_16x16x32_bf16 v[72:75], v[152:155], v[216:219], v[72:75]
	v_mfma_f32_16x16x32_bf16 v[68:71], v[160:163], v[216:219], v[68:71]
	s_setprio 0
	s_barrier
	s_add_i32 s53, s53, s41
	v_lshl_add_u64 v[198:199], s[34:35], 0, v[166:167]
	s_mov_b32 m0, s53
	ds_read_b128 v[176:179], v184 offset:16384
	ds_read_b128 v[180:183], v184 offset:17408
	ds_read_b128 v[186:189], v184 offset:18432
	ds_read_b128 v[190:193], v184 offset:19456
	ds_read_b128 v[194:197], v184 offset:20480
	ds_read_b128 v[208:211], v184 offset:21504
	ds_read_b128 v[212:215], v184 offset:22528
	ds_read_b128 v[216:219], v184 offset:23552
	global_load_lds_dwordx4 v[198:199], off
	s_add_i32 m0, s53, 0x2000
	s_add_u32 s76, s34, 0x40000
	v_lshl_add_u64 v[202:203], s[34:35], 0, v[170:171]
	s_addc_u32 s77, s35, 0
	s_add_i32 s53, s66, s41
	global_load_lds_dwordx4 v[202:203], off
	v_lshl_add_u64 v[220:221], s[76:77], 0, v[166:167]
	s_mov_b32 m0, s53
	v_lshl_add_u64 v[222:223], s[36:37], 0, v[168:169]
	global_load_lds_dwordx4 v[220:221], off
	v_lshl_add_u64 v[220:221], s[76:77], 0, v[170:171]
	s_add_i32 m0, s53, 0x2000
	s_nop 0
	global_load_lds_dwordx4 v[220:221], off
	v_lshl_add_u64 v[220:221], s[36:37], 0, v[164:165]
	s_mov_b32 m0, s45
	s_nop 0
	global_load_lds_dwordx4 v[220:221], off
	s_mov_b32 m0, s46
	s_nop 0
	global_load_lds_dwordx4 v[222:223], off
	s_waitcnt vmcnt(8)
	s_waitcnt lgkmcnt(0)
	s_barrier
; #define PG8_STAGE(bufoff, gbase, voff) do { _Pragma("unroll") for (int _i = 0; _i < 2; ++_i) \
;         __builtin_amdgcn_global_load_lds((const unsigned*)((const char*)(gbase) + (voff)[_i]), (LAS unsigned*)(lds + (bufoff) + ldsw + _i * 8192), 16, 0, 0); } while (0)
; #define PG8_LDA(dst, b, h) do { _Pragma("unroll") for (int m = 0; m < 4; ++m) _Pragma("unroll") for (int k = 0; k < 2; ++k) dst[m][k] = *(const LAS bf16x8*)(lds + PG8_SA(b, h) + aoff + m * 2048 + k * 1024); } while (0)
; #define PG8_LDB(dst, b, h) do { _Pragma("unroll") for (int n = 0; n < 2; ++n) _Pragma("unroll") for (int k = 0; k < 2; ++k) dst[n][k] = *(const LAS bf16x8*)(lds + PG8_SB(b, h) + boff + n * 2048 + k * 1024); } while (0)
; #define PG8_MMA(ai, bj, At, Bt) do { __builtin_amdgcn_s_setprio(1); _Pragma("unroll") for (int m = 0; m < 4; ++m) _Pragma("unroll") for (int n = 0; n < 2; ++n) _Pragma("unroll") for (int k = 0; k < 2; ++k) \
;         acc[ai][bj][m][n] = __builtin_amdgcn_mfma_f32_16x16x32_bf16(Bt[n][k], At[m][k], acc[ai][bj][m][n], 0, 0, 0); __builtin_amdgcn_s_setprio(0); } while (0)
; #define PG8_WAIT_V(n) asm volatile("s_waitcnt vmcnt(" #n ")" ::: "memory")
; #define PG8_WAIT_L(n) asm volatile("s_waitcnt lgkmcnt(" #n ")" ::: "memory")
; #define PG8_BAR __builtin_amdgcn_s_barrier()
; #define PG8_SCHED __builtin_amdgcn_sched_barrier(0)
; template <class Epi, class Sched, bool HALFN = false>
; __device__ __forceinline__ void gemm_phase(LAS unsigned char* lds, const Gemm g, const Sched& S, const Epi& E, int wave_s) {
;     ...
;             PG8_LDA(At, 0, 1); PG8_STAGE(PG8_SB(0, 0), b2, voffB); PG8_STAGE(PG8_SB(0, 1), b2 + bh1, voffB); PG8_STAGE(PG8_SA(0, 0), a2, voffA);
;             PG8_WAIT_V(8); PG8_WAIT_L(0); PG8_BAR; PG8_MMA(1, 0, At, B0); if (!HALFN) PG8_MMA(1, 1, At, B1); PG8_BAR; PG8_SCHED;
;             PG8_LDB(B0, 1, 0); if (!HALFN) PG8_LDB(B1, 1, 1); PG8_SCHED; PG8_LDA(At, 1, 0); PG8_STAGE(PG8_SA(0, 1), a2 + hstep, voffA);
;             PG8_WAIT_V(8); PG8_WAIT_L(0); PG8_BAR; PG8_MMA(0, 0, At, B0); if (!HALFN) PG8_MMA(0, 1, At, B1); PG8_BAR; PG8_SCHED;
	s_setprio 1
	v_mfma_f32_16x16x32_bf16 v[64:67], v[132:135], v[176:179], v[64:67]
	v_mfma_f32_16x16x32_bf16 v[60:63], v[140:143], v[176:179], v[60:63]
	v_mfma_f32_16x16x32_bf16 v[48:51], v[132:135], v[186:189], v[48:51]
	v_mfma_f32_16x16x32_bf16 v[44:47], v[140:143], v[186:189], v[44:47]
	v_mfma_f32_16x16x32_bf16 v[32:35], v[132:135], v[194:197], v[32:35]
	v_mfma_f32_16x16x32_bf16 v[28:31], v[140:143], v[194:197], v[28:31]
	v_mfma_f32_16x16x32_bf16 v[14:17], v[132:135], v[212:215], v[14:17]
	v_mfma_f32_16x16x32_bf16 v[10:13], v[140:143], v[212:215], v[10:13]
	v_mfma_f32_16x16x32_bf16 v[64:67], v[136:139], v[180:183], v[64:67]
	v_mfma_f32_16x16x32_bf16 v[60:63], v[144:147], v[180:183], v[60:63]
	v_mfma_f32_16x16x32_bf16 v[48:51], v[136:139], v[190:193], v[48:51]
	v_mfma_f32_16x16x32_bf16 v[44:47], v[144:147], v[190:193], v[44:47]
	v_mfma_f32_16x16x32_bf16 v[32:35], v[136:139], v[208:211], v[32:35]
	v_mfma_f32_16x16x32_bf16 v[28:31], v[144:147], v[208:211], v[28:31]
	v_mfma_f32_16x16x32_bf16 v[14:17], v[136:139], v[216:219], v[14:17]
	v_mfma_f32_16x16x32_bf16 v[10:13], v[144:147], v[216:219], v[10:13]
	s_setprio 0
	s_setprio 1
	v_mfma_f32_16x16x32_bf16 v[56:59], v[148:151], v[176:179], v[56:59]
	v_mfma_f32_16x16x32_bf16 v[52:55], v[156:159], v[176:179], v[52:55]
	v_mfma_f32_16x16x32_bf16 v[40:43], v[148:151], v[186:189], v[40:43]
	v_mfma_f32_16x16x32_bf16 v[36:39], v[156:159], v[186:189], v[36:39]
	v_mfma_f32_16x16x32_bf16 v[24:27], v[148:151], v[194:197], v[24:27]
	v_mfma_f32_16x16x32_bf16 v[20:23], v[156:159], v[194:197], v[20:23]
	v_mfma_f32_16x16x32_bf16 v[6:9], v[148:151], v[212:215], v[6:9]
	v_mfma_f32_16x16x32_bf16 v[2:5], v[156:159], v[212:215], v[2:5]
	v_mfma_f32_16x16x32_bf16 v[56:59], v[152:155], v[180:183], v[56:59]
	v_mfma_f32_16x16x32_bf16 v[52:55], v[160:163], v[180:183], v[52:55]
	v_mfma_f32_16x16x32_bf16 v[40:43], v[152:155], v[190:193], v[40:43]
	v_mfma_f32_16x16x32_bf16 v[36:39], v[160:163], v[190:193], v[36:39]
	v_mfma_f32_16x16x32_bf16 v[24:27], v[152:155], v[208:211], v[24:27]
	v_mfma_f32_16x16x32_bf16 v[20:23], v[160:163], v[208:211], v[20:23]
	v_mfma_f32_16x16x32_bf16 v[6:9], v[152:155], v[216:219], v[6:9]
	v_mfma_f32_16x16x32_bf16 v[2:5], v[160:163], v[216:219], v[2:5]
	s_setprio 0
	s_barrier
	s_add_i32 s53, 0, 0x18000
	v_add_u32_e32 v18, s53, v1
	s_add_i32 s66, 0, 0x1c000
	ds_read_b128 v[132:135], v18
	ds_read_b128 v[136:139], v18 offset:1024
	ds_read_b128 v[140:143], v18 offset:2048
	ds_read_b128 v[144:147], v18 offset:3072
	v_add_u32_e32 v18, s66, v1
	ds_read_b128 v[148:151], v18
	ds_read_b128 v[152:155], v18 offset:1024
	ds_read_b128 v[156:159], v18 offset:2048
	ds_read_b128 v[160:163], v18 offset:3072
	s_add_u32 s36, s36, 0x40000
	s_addc_u32 s37, s37, 0
	s_mov_b32 m0, s47
	v_lshl_add_u64 v[224:225], s[36:37], 0, v[164:165]
	ds_read_b128 v[176:179], v184 offset:32768
	ds_read_b128 v[180:183], v184 offset:33792
	ds_read_b128 v[186:189], v184 offset:34816
	ds_read_b128 v[190:193], v184 offset:35840
	ds_read_b128 v[194:197], v184 offset:36864
	ds_read_b128 v[208:211], v184 offset:37888
	ds_read_b128 v[212:215], v184 offset:38912
	ds_read_b128 v[216:219], v184 offset:39936
	global_load_lds_dwordx4 v[224:225], off
	v_lshl_add_u64 v[224:225], s[36:37], 0, v[168:169]
	s_mov_b32 m0, s55
	s_nop 0
	global_load_lds_dwordx4 v[224:225], off
	s_waitcnt vmcnt(8)
	s_waitcnt lgkmcnt(0)
	s_barrier
	s_setprio 1
	v_mfma_f32_16x16x32_bf16 v[128:131], v[132:135], v[176:179], v[128:131]
	v_mfma_f32_16x16x32_bf16 v[124:127], v[140:143], v[176:179], v[124:127]
	v_mfma_f32_16x16x32_bf16 v[112:115], v[132:135], v[186:189], v[112:115]
	v_mfma_f32_16x16x32_bf16 v[108:111], v[140:143], v[186:189], v[108:111]
	v_mfma_f32_16x16x32_bf16 v[96:99], v[132:135], v[194:197], v[96:99]
	v_mfma_f32_16x16x32_bf16 v[92:95], v[140:143], v[194:197], v[92:95]
	v_mfma_f32_16x16x32_bf16 v[80:83], v[132:135], v[212:215], v[80:83]
	v_mfma_f32_16x16x32_bf16 v[76:79], v[140:143], v[212:215], v[76:79]
	v_mfma_f32_16x16x32_bf16 v[128:131], v[136:139], v[180:183], v[128:131]
	v_mfma_f32_16x16x32_bf16 v[124:127], v[144:147], v[180:183], v[124:127]
	v_mfma_f32_16x16x32_bf16 v[112:115], v[136:139], v[190:193], v[112:115]
	v_mfma_f32_16x16x32_bf16 v[108:111], v[144:147], v[190:193], v[108:111]
	v_mfma_f32_16x16x32_bf16 v[96:99], v[136:139], v[208:211], v[96:99]
	v_mfma_f32_16x16x32_bf16 v[92:95], v[144:147], v[208:211], v[92:95]
	v_mfma_f32_16x16x32_bf16 v[80:83], v[136:139], v[216:219], v[80:83]
	v_mfma_f32_16x16x32_bf16 v[76:79], v[144:147], v[216:219], v[76:79]
	s_setprio 0
	s_setprio 1
	v_mfma_f32_16x16x32_bf16 v[120:123], v[148:151], v[176:179], v[120:123]
	v_mfma_f32_16x16x32_bf16 v[116:119], v[156:159], v[176:179], v[116:119]
	v_mfma_f32_16x16x32_bf16 v[104:107], v[148:151], v[186:189], v[104:107]
	v_mfma_f32_16x16x32_bf16 v[100:103], v[156:159], v[186:189], v[100:103]
	v_mfma_f32_16x16x32_bf16 v[88:91], v[148:151], v[194:197], v[88:91]
	v_mfma_f32_16x16x32_bf16 v[84:87], v[156:159], v[194:197], v[84:87]
	v_mfma_f32_16x16x32_bf16 v[72:75], v[148:151], v[212:215], v[72:75]
	v_mfma_f32_16x16x32_bf16 v[68:71], v[156:159], v[212:215], v[68:71]
	v_mfma_f32_16x16x32_bf16 v[120:123], v[152:155], v[180:183], v[120:123]
	v_mfma_f32_16x16x32_bf16 v[116:119], v[160:163], v[180:183], v[116:119]
	v_mfma_f32_16x16x32_bf16 v[104:107], v[152:155], v[190:193], v[104:107]
	v_mfma_f32_16x16x32_bf16 v[100:103], v[160:163], v[190:193], v[100:103]
	v_mfma_f32_16x16x32_bf16 v[88:91], v[152:155], v[208:211], v[88:91]
	v_mfma_f32_16x16x32_bf16 v[84:87], v[160:163], v[208:211], v[84:87]
	v_mfma_f32_16x16x32_bf16 v[72:75], v[152:155], v[216:219], v[72:75]
	v_mfma_f32_16x16x32_bf16 v[68:71], v[160:163], v[216:219], v[68:71]
	s_setprio 0
	s_barrier
; #define PG8_STAGE(bufoff, gbase, voff) do { _Pragma("unroll") for (int _i = 0; _i < 2; ++_i) \
;         __builtin_amdgcn_global_load_lds((const unsigned*)((const char*)(gbase) + (voff)[_i]), (LAS unsigned*)(lds + (bufoff) + ldsw + _i * 8192), 16, 0, 0); } while (0)
; #define PG8_LDA(dst, b, h) do { _Pragma("unroll") for (int m = 0; m < 4; ++m) _Pragma("unroll") for (int k = 0; k < 2; ++k) dst[m][k] = *(const LAS bf16x8*)(lds + PG8_SA(b, h) + aoff + m * 2048 + k * 1024); } while (0)
; #define PG8_MMA(ai, bj, At, Bt) do { __builtin_amdgcn_s_setprio(1); _Pragma("unroll") for (int m = 0; m < 4; ++m) _Pragma("unroll") for (int n = 0; n < 2; ++n) _Pragma("unroll") for (int k = 0; k < 2; ++k) \
;         acc[ai][bj][m][n] = __builtin_amdgcn_mfma_f32_16x16x32_bf16(Bt[n][k], At[m][k], acc[ai][bj][m][n], 0, 0, 0); __builtin_amdgcn_s_setprio(0); } while (0)
; #define PG8_WAIT_V(n) asm volatile("s_waitcnt vmcnt(" #n ")" ::: "memory")
; #define PG8_WAIT_L(n) asm volatile("s_waitcnt lgkmcnt(" #n ")" ::: "memory")
; #define PG8_BAR __builtin_amdgcn_s_barrier()
; #define PG8_SCHED __builtin_amdgcn_sched_barrier(0)
; template <class Epi, class Sched, bool HALFN = false>
; __device__ __forceinline__ void gemm_phase(LAS unsigned char* lds, const Gemm g, const Sched& S, const Epi& E, int wave_s) {
;     ...
;             PG8_LDA(At, 1, 1); PG8_STAGE(PG8_SB(1, 0), b3, voffB); PG8_STAGE(PG8_SB(1, 1), b3 + bh1, voffB); PG8_STAGE(PG8_SA(1, 0), a3, voffA);
;             PG8_WAIT_V(8); PG8_WAIT_L(0); PG8_BAR; PG8_MMA(1, 0, At, B0); if (!HALFN) PG8_MMA(1, 1, At, B1); PG8_BAR; PG8_SCHED;
;         }
	s_add_i32 s36, s53, s41
	v_lshl_add_u64 v[198:199], v[198:199], 0, s[50:51]
	s_mov_b32 m0, s36
	ds_read_b128 v[176:179], v184 offset:49152
	ds_read_b128 v[180:183], v184 offset:50176
	ds_read_b128 v[186:189], v184 offset:51200
	ds_read_b128 v[190:193], v184 offset:52224
	ds_read_b128 v[194:197], v184 offset:53248
	ds_read_b128 v[208:211], v184 offset:54272
	ds_read_b128 v[212:215], v184 offset:55296
	ds_read_b128 v[216:219], v184 offset:56320
	global_load_lds_dwordx4 v[198:199], off
	s_add_i32 m0, s36, 0x2000
	s_add_u32 s34, s34, 0x40080
	v_lshl_add_u64 v[198:199], v[202:203], 0, s[50:51]
	s_addc_u32 s35, s35, 0
	s_add_i32 s36, s66, s41
	global_load_lds_dwordx4 v[198:199], off
	v_lshl_add_u64 v[198:199], s[34:35], 0, v[166:167]
	s_mov_b32 m0, s36
	s_nop 0
	global_load_lds_dwordx4 v[198:199], off
	v_lshl_add_u64 v[198:199], s[34:35], 0, v[170:171]
	s_add_i32 m0, s36, 0x2000
	s_nop 0
	global_load_lds_dwordx4 v[198:199], off
	v_lshl_add_u64 v[198:199], v[220:221], 0, s[50:51]
	s_mov_b32 m0, s64
	s_nop 0
	global_load_lds_dwordx4 v[198:199], off
	v_lshl_add_u64 v[198:199], v[222:223], 0, s[50:51]
	s_mov_b32 m0, s65
	s_nop 0
	global_load_lds_dwordx4 v[198:199], off
	s_waitcnt vmcnt(8)
	s_waitcnt lgkmcnt(0)
	s_barrier
	s_setprio 1
	v_mfma_f32_16x16x32_bf16 v[64:67], v[132:135], v[176:179], v[64:67]
	v_mfma_f32_16x16x32_bf16 v[60:63], v[140:143], v[176:179], v[60:63]
	v_mfma_f32_16x16x32_bf16 v[48:51], v[132:135], v[186:189], v[48:51]
	v_mfma_f32_16x16x32_bf16 v[44:47], v[140:143], v[186:189], v[44:47]
	v_mfma_f32_16x16x32_bf16 v[32:35], v[132:135], v[194:197], v[32:35]
	v_mfma_f32_16x16x32_bf16 v[28:31], v[140:143], v[194:197], v[28:31]
	v_mfma_f32_16x16x32_bf16 v[14:17], v[132:135], v[212:215], v[14:17]
	v_mfma_f32_16x16x32_bf16 v[10:13], v[140:143], v[212:215], v[10:13]
	v_mfma_f32_16x16x32_bf16 v[64:67], v[136:139], v[180:183], v[64:67]
	v_mfma_f32_16x16x32_bf16 v[60:63], v[144:147], v[180:183], v[60:63]
	v_mfma_f32_16x16x32_bf16 v[48:51], v[136:139], v[190:193], v[48:51]
	v_mfma_f32_16x16x32_bf16 v[44:47], v[144:147], v[190:193], v[44:47]
	v_mfma_f32_16x16x32_bf16 v[32:35], v[136:139], v[208:211], v[32:35]
	v_mfma_f32_16x16x32_bf16 v[28:31], v[144:147], v[208:211], v[28:31]
	v_mfma_f32_16x16x32_bf16 v[14:17], v[136:139], v[216:219], v[14:17]
	v_mfma_f32_16x16x32_bf16 v[10:13], v[144:147], v[216:219], v[10:13]
	s_setprio 0
	s_setprio 1
	v_mfma_f32_16x16x32_bf16 v[56:59], v[148:151], v[176:179], v[56:59]
	v_mfma_f32_16x16x32_bf16 v[52:55], v[156:159], v[176:179], v[52:55]
	v_mfma_f32_16x16x32_bf16 v[40:43], v[148:151], v[186:189], v[40:43]
	v_mfma_f32_16x16x32_bf16 v[36:39], v[156:159], v[186:189], v[36:39]
	v_mfma_f32_16x16x32_bf16 v[24:27], v[148:151], v[194:197], v[24:27]
	v_mfma_f32_16x16x32_bf16 v[20:23], v[156:159], v[194:197], v[20:23]
	v_mfma_f32_16x16x32_bf16 v[6:9], v[148:151], v[212:215], v[6:9]
	v_mfma_f32_16x16x32_bf16 v[2:5], v[156:159], v[212:215], v[2:5]
	v_mfma_f32_16x16x32_bf16 v[56:59], v[152:155], v[180:183], v[56:59]
	v_mfma_f32_16x16x32_bf16 v[52:55], v[160:163], v[180:183], v[52:55]
	v_mfma_f32_16x16x32_bf16 v[40:43], v[152:155], v[190:193], v[40:43]
	v_mfma_f32_16x16x32_bf16 v[36:39], v[160:163], v[190:193], v[36:39]
	v_mfma_f32_16x16x32_bf16 v[24:27], v[152:155], v[208:211], v[24:27]
	v_mfma_f32_16x16x32_bf16 v[20:23], v[160:163], v[208:211], v[20:23]
	v_mfma_f32_16x16x32_bf16 v[6:9], v[152:155], v[216:219], v[6:9]
	v_mfma_f32_16x16x32_bf16 v[2:5], v[160:163], v[216:219], v[2:5]
	s_setprio 0
	s_barrier
	s_add_i32 s52, s52, 2
	s_add_u32 s6, s6, 0x100
	s_addc_u32 s7, s7, 0
	s_add_u32 s42, s42, 0x100
	s_addc_u32 s48, s48, 0
	s_cmp_gt_u32 s52, 13
	s_cbranch_scc0 .LBB0_985
	s_and_b64 vcc, exec, s[20:21]
	s_cbranch_vccz .LBB0_988
	s_barrier
